# UPCONV epilogue: the two 8-byte stores per position paired into one 16-byte store
# speedup vs baseline: 1.0094x; 1.0094x over previous
;     __device__ __forceinline__ void operator()(const f32x4 (&acc)[2][2][4][2], const Unit& u, int wr, int wc, int fr, int fq) const {
;     ...
;                 for (int m = 0; m < 4; ++m) rs[ai][m] = rsqrtf(ss[row0 + ai * HALF + m * 16] * (1.f / 2048.f) + 1e-6f);
; #pragma unroll
;             for (int ai = 0; ai < 2; ++ai) {
;                 const int slab = u.pm * 4 + ai * 2 + wr;
;                 if (fr < 2) {
; #pragma unroll
;                     for (int bj = 0; bj < 2; ++bj)
; #pragma unroll
;                         for (int n = 0; n < 2; ++n) *(f32x4*)(raw + (size_t)(slab * 4 + fr) * NUPc + tcol + bj * 128 + 4 * n) = acc[ai][bj][0][n] * rs[ai][0];
;                 }
;                 if (fr >= 14) {
; #pragma unroll
;                     for (int bj = 0; bj < 2; ++bj)
; #pragma unroll
;                         for (int n = 0; n < 2; ++n) *(f32x4*)(raw + (size_t)(slab * 4 + fr - 12) * NUPc + tcol + bj * 128 + 4 * n) = acc[ai][bj][3][n] * rs[ai][3];
;                 }
;             }
; #pragma unroll
;             for (int n = 0; n < 2; ++n) {
;                 const int c = cgl + 4 * n;
;                 const f32x4 wg0 = *(const f32x4*)(bias + c), wg1 = *(const f32x4*)(bias + NUPc + c), wg2 = *(const f32x4*)(bias + 2 * NUPc + c), bg = *(const f32x4*)(xin + c);
;                 const f32x4 wv0 = *(const f32x4*)(bias + DFFc + c), wv1 = *(const f32x4*)(bias + NUPc + DFFc + c), wv2 = *(const f32x4*)(bias + 2 * NUPc + DFFc + c), bv = *(const f32x4*)(xin + DFFc + c);
; #pragma unroll
;                 for (int ai = 0; ai < 2; ++ai) {
;                     f32x4 pg1 = (f32x4){0.f, 0.f, 0.f, 0.f}, pg2 = pg1, pv1 = pg1, pv2 = pg1;
; #pragma unroll
;                     for (int m = 0; m < 4; ++m) {
;                         const f32x4 g = acc[ai][0][m][n] * rs[ai][m], v = acc[ai][1][m][n] * rs[ai][m];
;                         const f32x4 g1 = dpp4<0x121>(g), g2 = dpp4<0x122>(g), v1 = dpp4<0x121>(v), v2 = dpp4<0x122>(v);
;                         const f32x4 gp1 = (fr >= 1) ? g1 : pg1, gp2 = (fr >= 2) ? g2 : pg2, vp1 = (fr >= 1) ? v1 : pv1, vp2 = (fr >= 2) ? v2 : pv2;
;                         const f32x4 cgt = bg + wg0 * g + wg1 * gp1 + wg2 * gp2, cvl = bv + wv0 * v + wv1 * vp1 + wv2 * vp2;
;                         const f32x4 o = gelu4(cgt) * cvl;
;                         typedef unsigned u32x2e __attribute__((ext_vector_type(2)));
.LBB0_54:
	s_or_b64 exec, exec, s[48:49]
	v_fmamk_f32 v187, v187, 0x3a000000, v197
	v_fmamk_f32 v179, v179, 0x3a000000, v197
	v_fmamk_f32 v185, v185, 0x3a000000, v197
	v_fmamk_f32 v183, v183, 0x3a000000, v197
	v_cmp_gt_f32_e32 vcc, s67, v187
	v_cmp_gt_f32_e64 s[48:49], s67, v179
	v_cmp_gt_f32_e64 s[50:51], s67, v185
	v_cmp_gt_f32_e64 s[52:53], s67, v183
	v_mul_f32_e32 v181, 0x4b800000, v187
	v_mul_f32_e32 v189, 0x4b800000, v179
	v_mul_f32_e32 v191, 0x4b800000, v185
	v_mul_f32_e32 v193, 0x4b800000, v183
	v_cndmask_b32_e32 v187, v187, v181, vcc
	v_cndmask_b32_e64 v179, v179, v189, s[48:49]
	v_cndmask_b32_e64 v185, v185, v191, s[50:51]
	v_cndmask_b32_e64 v183, v183, v193, s[52:53]
	v_rsq_f32_e32 v187, v187
	v_rsq_f32_e32 v179, v179
	v_rsq_f32_e32 v185, v185
	v_rsq_f32_e32 v183, v183
	v_mul_f32_e32 v181, 0x45800000, v187
	v_mul_f32_e32 v189, 0x45800000, v179
	v_mul_f32_e32 v191, 0x45800000, v185
	v_mul_f32_e32 v193, 0x45800000, v183
	v_cndmask_b32_e32 v190, v187, v181, vcc
	v_cndmask_b32_e64 v192, v179, v189, s[48:49]
	v_cndmask_b32_e64 v180, v185, v191, s[50:51]
	v_cndmask_b32_e64 v200, v183, v193, s[52:53]
	v_mov_b32_e32 v132, 0xbdd2d3e8
	v_mov_b32_e32 v250, 1.0
	v_lshlrev_b32_e32 v199, 1, v201
	s_movk_i32 s41, 0x2c00
	v_mad_u32_u24 v199, v186, s41, v199
	v_pk_mul_f32 v[154:155], v[154:155], v[188:189] op_sel_hi:[1,0]
	v_pk_mul_f32 v[156:157], v[156:157], v[188:189] op_sel_hi:[1,0]
	v_pk_mul_f32 v[134:135], v[134:135], v[188:189] op_sel_hi:[1,0]
	v_pk_mul_f32 v[136:137], v[136:137], v[188:189] op_sel_hi:[1,0]
	v_pk_fma_f32 v[106:107], v[154:155], v[218:219], v[222:223]
	v_pk_fma_f32 v[108:109], v[156:157], v[220:221], v[224:225]
	v_pk_fma_f32 v[110:111], v[134:135], v[234:235], v[238:239]
	v_pk_fma_f32 v[112:113], v[136:137], v[236:237], v[240:241]
	v_fmac_f32_dpp v106, v154, v226 row_shr:1 row_mask:0xf bank_mask:0xf
	v_fmac_f32_dpp v107, v155, v227 row_shr:1 row_mask:0xf bank_mask:0xf
	v_fmac_f32_dpp v108, v156, v228 row_shr:1 row_mask:0xf bank_mask:0xf
	v_fmac_f32_dpp v109, v157, v229 row_shr:1 row_mask:0xf bank_mask:0xf
	v_fmac_f32_dpp v110, v134, v242 row_shr:1 row_mask:0xf bank_mask:0xf
	v_fmac_f32_dpp v111, v135, v243 row_shr:1 row_mask:0xf bank_mask:0xf
	v_fmac_f32_dpp v112, v136, v244 row_shr:1 row_mask:0xf bank_mask:0xf
	v_fmac_f32_dpp v113, v137, v245 row_shr:1 row_mask:0xf bank_mask:0xf
	v_fmac_f32_dpp v106, v154, v230 row_shr:2 row_mask:0xf bank_mask:0xf
	v_fmac_f32_dpp v107, v155, v231 row_shr:2 row_mask:0xf bank_mask:0xf
	v_fmac_f32_dpp v108, v156, v232 row_shr:2 row_mask:0xf bank_mask:0xf
	v_fmac_f32_dpp v109, v157, v233 row_shr:2 row_mask:0xf bank_mask:0xf
	v_fmac_f32_dpp v110, v134, v246 row_shr:2 row_mask:0xf bank_mask:0xf
	v_fmac_f32_dpp v111, v135, v247 row_shr:2 row_mask:0xf bank_mask:0xf
	v_fmac_f32_dpp v112, v136, v248 row_shr:2 row_mask:0xf bank_mask:0xf
	v_fmac_f32_dpp v113, v137, v249 row_shr:2 row_mask:0xf bank_mask:0xf
	v_pk_mul_f32 v[114:115], v[106:107], v[106:107]
	v_pk_mul_f32 v[116:117], v[108:109], v[108:109]
	v_pk_fma_f32 v[114:115], v[114:115], v[132:133], v[196:197] op_sel_hi:[1,0,0]
	v_pk_fma_f32 v[116:117], v[116:117], v[132:133], v[196:197] op_sel_hi:[1,0,0]
	v_pk_mul_f32 v[114:115], v[106:107], v[114:115]
	v_pk_mul_f32 v[116:117], v[108:109], v[116:117]
	v_exp_f32_e32 v114, v114
	v_exp_f32_e32 v115, v115
	v_exp_f32_e32 v116, v116
	v_exp_f32_e32 v117, v117
	v_pk_add_f32 v[114:115], v[114:115], v[250:251] op_sel_hi:[1,0]
	v_pk_add_f32 v[116:117], v[116:117], v[250:251] op_sel_hi:[1,0]
	v_rcp_f32_e32 v114, v114
	v_rcp_f32_e32 v115, v115
	v_rcp_f32_e32 v116, v116
	v_rcp_f32_e32 v117, v117
	v_pk_mul_f32 v[114:115], v[106:107], v[114:115]
	v_pk_mul_f32 v[116:117], v[108:109], v[116:117]
	v_pk_mul_f32 v[114:115], v[110:111], v[114:115]
	v_pk_mul_f32 v[116:117], v[112:113], v[116:117]
	v_cvt_pk_bf16_f32 v114, v114, v115
	v_cvt_pk_bf16_f32 v115, v116, v117
	v_mov_b32_e32 v179, v114
	v_mov_b32_e32 v181, v115
	v_pk_mul_f32 v[150:151], v[150:151], v[190:191] op_sel_hi:[1,0]
	v_pk_mul_f32 v[152:153], v[152:153], v[190:191] op_sel_hi:[1,0]
	v_pk_mul_f32 v[146:147], v[146:147], v[190:191] op_sel_hi:[1,0]
	v_pk_mul_f32 v[148:149], v[148:149], v[190:191] op_sel_hi:[1,0]
	v_pk_fma_f32 v[118:119], v[150:151], v[218:219], v[222:223]
	v_pk_fma_f32 v[120:121], v[152:153], v[220:221], v[224:225]
	v_pk_fma_f32 v[122:123], v[146:147], v[234:235], v[238:239]
	v_pk_fma_f32 v[124:125], v[148:149], v[236:237], v[240:241]
	v_fmac_f32_dpp v118, v150, v226 row_shr:1 row_mask:0xf bank_mask:0xf
	v_fmac_f32_dpp v119, v151, v227 row_shr:1 row_mask:0xf bank_mask:0xf
	v_fmac_f32_dpp v120, v152, v228 row_shr:1 row_mask:0xf bank_mask:0xf
	v_fmac_f32_dpp v121, v153, v229 row_shr:1 row_mask:0xf bank_mask:0xf
	v_fmac_f32_dpp v122, v146, v242 row_shr:1 row_mask:0xf bank_mask:0xf
	v_fmac_f32_dpp v123, v147, v243 row_shr:1 row_mask:0xf bank_mask:0xf
	v_fmac_f32_dpp v124, v148, v244 row_shr:1 row_mask:0xf bank_mask:0xf
	v_fmac_f32_dpp v125, v149, v245 row_shr:1 row_mask:0xf bank_mask:0xf
	v_fmac_f32_dpp v118, v150, v230 row_shr:2 row_mask:0xf bank_mask:0xf
	v_fmac_f32_dpp v119, v151, v231 row_shr:2 row_mask:0xf bank_mask:0xf
	v_fmac_f32_dpp v120, v152, v232 row_shr:2 row_mask:0xf bank_mask:0xf
	v_fmac_f32_dpp v121, v153, v233 row_shr:2 row_mask:0xf bank_mask:0xf
	v_fmac_f32_dpp v122, v146, v246 row_shr:2 row_mask:0xf bank_mask:0xf
	v_fmac_f32_dpp v123, v147, v247 row_shr:2 row_mask:0xf bank_mask:0xf
	v_fmac_f32_dpp v124, v148, v248 row_shr:2 row_mask:0xf bank_mask:0xf
	v_fmac_f32_dpp v125, v149, v249 row_shr:2 row_mask:0xf bank_mask:0xf
	v_fmac_f32_dpp v118, v154, v226 row_shl:15 row_mask:0xf bank_mask:0xf
	v_fmac_f32_dpp v119, v155, v227 row_shl:15 row_mask:0xf bank_mask:0xf
; __device__ __forceinline__ unsigned cvt_pk_bf16(float lo, float hi) { unsigned r; asm volatile("v_cvt_pk_bf16_f32 %0, %1, %2" : "=v"(r) : "v"(lo), "v"(hi)); return r; }
; __device__ __forceinline__ f32x4 gelu4(f32x4 v) { return (f32x4){gelu_t(v[0]), gelu_t(v[1]), gelu_t(v[2]), gelu_t(v[3])}; }
; template <int CTRL> __device__ __forceinline__ f32x4 dpp4(f32x4 v) { return (f32x4){dpp_f<CTRL>(v[0]), dpp_f<CTRL>(v[1]), dpp_f<CTRL>(v[2]), dpp_f<CTRL>(v[3])}; }
;     __device__ __forceinline__ void operator()(const f32x4 (&acc)[2][2][4][2], const Unit& u, int wr, int wc, int fr, int fq) const {
;     ...
;                     for (int m = 0; m < 4; ++m) {
;                         const f32x4 g = acc[ai][0][m][n] * rs[ai][m], v = acc[ai][1][m][n] * rs[ai][m];
;                         const f32x4 g1 = dpp4<0x121>(g), g2 = dpp4<0x122>(g), v1 = dpp4<0x121>(v), v2 = dpp4<0x122>(v);
;                         const f32x4 gp1 = (fr >= 1) ? g1 : pg1, gp2 = (fr >= 2) ? g2 : pg2, vp1 = (fr >= 1) ? v1 : pv1, vp2 = (fr >= 2) ? v2 : pv2;
;                         const f32x4 cgt = bg + wg0 * g + wg1 * gp1 + wg2 * gp2, cvl = bv + wv0 * v + wv1 * vp1 + wv2 * vp2;
;                         const f32x4 o = gelu4(cgt) * cvl;
;                         typedef unsigned u32x2e __attribute__((ext_vector_type(2)));
;                         u32x2e w; w.x = cvt_pk_bf16(o[0], o[1]); w.y = cvt_pk_bf16(o[2], o[3]);
;                         if (!(m == 0 && fr < 2)) *(u32x2e*)((bf16_t*)O + (size_t)(row0 + ai * HALF + m * 16) * DFFc + c) = w;
;                         pg1 = g1; pg2 = g2; pv1 = v1; pv2 = v2;
	v_fmac_f32_dpp v120, v156, v228 row_shl:15 row_mask:0xf bank_mask:0xf
	v_fmac_f32_dpp v121, v157, v229 row_shl:15 row_mask:0xf bank_mask:0xf
	v_fmac_f32_dpp v122, v134, v242 row_shl:15 row_mask:0xf bank_mask:0xf
	v_fmac_f32_dpp v123, v135, v243 row_shl:15 row_mask:0xf bank_mask:0xf
	v_fmac_f32_dpp v124, v136, v244 row_shl:15 row_mask:0xf bank_mask:0xf
	v_fmac_f32_dpp v125, v137, v245 row_shl:15 row_mask:0xf bank_mask:0xf
	v_fmac_f32_dpp v118, v154, v230 row_shl:14 row_mask:0xf bank_mask:0xf
	v_fmac_f32_dpp v119, v155, v231 row_shl:14 row_mask:0xf bank_mask:0xf
	v_fmac_f32_dpp v120, v156, v232 row_shl:14 row_mask:0xf bank_mask:0xf
	v_fmac_f32_dpp v121, v157, v233 row_shl:14 row_mask:0xf bank_mask:0xf
	v_fmac_f32_dpp v122, v134, v246 row_shl:14 row_mask:0xf bank_mask:0xf
	v_fmac_f32_dpp v123, v135, v247 row_shl:14 row_mask:0xf bank_mask:0xf
	v_fmac_f32_dpp v124, v136, v248 row_shl:14 row_mask:0xf bank_mask:0xf
	v_fmac_f32_dpp v125, v137, v249 row_shl:14 row_mask:0xf bank_mask:0xf
	v_pk_mul_f32 v[126:127], v[118:119], v[118:119]
	v_pk_mul_f32 v[128:129], v[120:121], v[120:121]
	v_pk_fma_f32 v[126:127], v[126:127], v[132:133], v[196:197] op_sel_hi:[1,0,0]
	v_pk_fma_f32 v[128:129], v[128:129], v[132:133], v[196:197] op_sel_hi:[1,0,0]
	v_pk_mul_f32 v[126:127], v[118:119], v[126:127]
	v_pk_mul_f32 v[128:129], v[120:121], v[128:129]
	v_exp_f32_e32 v126, v126
	v_exp_f32_e32 v127, v127
	v_exp_f32_e32 v128, v128
	v_exp_f32_e32 v129, v129
	v_pk_add_f32 v[126:127], v[126:127], v[250:251] op_sel_hi:[1,0]
	v_pk_add_f32 v[128:129], v[128:129], v[250:251] op_sel_hi:[1,0]
	v_rcp_f32_e32 v126, v126
	v_rcp_f32_e32 v127, v127
	v_rcp_f32_e32 v128, v128
	v_rcp_f32_e32 v129, v129
	v_pk_mul_f32 v[126:127], v[118:119], v[126:127]
	v_pk_mul_f32 v[128:129], v[120:121], v[128:129]
	v_pk_mul_f32 v[126:127], v[122:123], v[126:127]
	v_pk_mul_f32 v[128:129], v[124:125], v[128:129]
	v_cvt_pk_bf16_f32 v126, v126, v127
	v_cvt_pk_bf16_f32 v127, v128, v129
	v_mov_b32_e32 v183, v126
	v_mov_b32_e32 v185, v127
	v_pk_mul_f32 v[142:143], v[142:143], v[192:193] op_sel_hi:[1,0]
	v_pk_mul_f32 v[144:145], v[144:145], v[192:193] op_sel_hi:[1,0]
	v_pk_mul_f32 v[138:139], v[138:139], v[192:193] op_sel_hi:[1,0]
	v_pk_mul_f32 v[140:141], v[140:141], v[192:193] op_sel_hi:[1,0]
	v_pk_fma_f32 v[106:107], v[142:143], v[218:219], v[222:223]
	v_pk_fma_f32 v[108:109], v[144:145], v[220:221], v[224:225]
	v_pk_fma_f32 v[110:111], v[138:139], v[234:235], v[238:239]
	v_pk_fma_f32 v[112:113], v[140:141], v[236:237], v[240:241]
	v_fmac_f32_dpp v106, v142, v226 row_shr:1 row_mask:0xf bank_mask:0xf
	v_fmac_f32_dpp v107, v143, v227 row_shr:1 row_mask:0xf bank_mask:0xf
	v_fmac_f32_dpp v108, v144, v228 row_shr:1 row_mask:0xf bank_mask:0xf
	v_fmac_f32_dpp v109, v145, v229 row_shr:1 row_mask:0xf bank_mask:0xf
	v_fmac_f32_dpp v110, v138, v242 row_shr:1 row_mask:0xf bank_mask:0xf
	v_fmac_f32_dpp v111, v139, v243 row_shr:1 row_mask:0xf bank_mask:0xf
	v_fmac_f32_dpp v112, v140, v244 row_shr:1 row_mask:0xf bank_mask:0xf
	v_fmac_f32_dpp v113, v141, v245 row_shr:1 row_mask:0xf bank_mask:0xf
	v_fmac_f32_dpp v106, v142, v230 row_shr:2 row_mask:0xf bank_mask:0xf
	v_fmac_f32_dpp v107, v143, v231 row_shr:2 row_mask:0xf bank_mask:0xf
	v_fmac_f32_dpp v108, v144, v232 row_shr:2 row_mask:0xf bank_mask:0xf
	v_fmac_f32_dpp v109, v145, v233 row_shr:2 row_mask:0xf bank_mask:0xf
	v_fmac_f32_dpp v110, v138, v246 row_shr:2 row_mask:0xf bank_mask:0xf
	v_fmac_f32_dpp v111, v139, v247 row_shr:2 row_mask:0xf bank_mask:0xf
	v_fmac_f32_dpp v112, v140, v248 row_shr:2 row_mask:0xf bank_mask:0xf
	v_fmac_f32_dpp v113, v141, v249 row_shr:2 row_mask:0xf bank_mask:0xf
	v_fmac_f32_dpp v106, v150, v226 row_shl:15 row_mask:0xf bank_mask:0xf
	v_fmac_f32_dpp v107, v151, v227 row_shl:15 row_mask:0xf bank_mask:0xf
	v_fmac_f32_dpp v108, v152, v228 row_shl:15 row_mask:0xf bank_mask:0xf
	v_fmac_f32_dpp v109, v153, v229 row_shl:15 row_mask:0xf bank_mask:0xf
	v_fmac_f32_dpp v110, v146, v242 row_shl:15 row_mask:0xf bank_mask:0xf
	v_fmac_f32_dpp v111, v147, v243 row_shl:15 row_mask:0xf bank_mask:0xf
	v_fmac_f32_dpp v112, v148, v244 row_shl:15 row_mask:0xf bank_mask:0xf
	v_fmac_f32_dpp v113, v149, v245 row_shl:15 row_mask:0xf bank_mask:0xf
	v_fmac_f32_dpp v106, v150, v230 row_shl:14 row_mask:0xf bank_mask:0xf
	v_fmac_f32_dpp v107, v151, v231 row_shl:14 row_mask:0xf bank_mask:0xf
	v_fmac_f32_dpp v108, v152, v232 row_shl:14 row_mask:0xf bank_mask:0xf
	v_fmac_f32_dpp v109, v153, v233 row_shl:14 row_mask:0xf bank_mask:0xf
	v_fmac_f32_dpp v110, v146, v246 row_shl:14 row_mask:0xf bank_mask:0xf
	v_fmac_f32_dpp v111, v147, v247 row_shl:14 row_mask:0xf bank_mask:0xf
	v_fmac_f32_dpp v112, v148, v248 row_shl:14 row_mask:0xf bank_mask:0xf
	v_fmac_f32_dpp v113, v149, v249 row_shl:14 row_mask:0xf bank_mask:0xf
	v_pk_mul_f32 v[114:115], v[106:107], v[106:107]
	v_pk_mul_f32 v[116:117], v[108:109], v[108:109]
	v_pk_fma_f32 v[114:115], v[114:115], v[132:133], v[196:197] op_sel_hi:[1,0,0]
	v_pk_fma_f32 v[116:117], v[116:117], v[132:133], v[196:197] op_sel_hi:[1,0,0]
	v_pk_mul_f32 v[114:115], v[106:107], v[114:115]
	v_pk_mul_f32 v[116:117], v[108:109], v[116:117]
	v_exp_f32_e32 v114, v114
	v_exp_f32_e32 v115, v115
	v_exp_f32_e32 v116, v116
	v_exp_f32_e32 v117, v117
	v_pk_add_f32 v[114:115], v[114:115], v[250:251] op_sel_hi:[1,0]
	v_pk_add_f32 v[116:117], v[116:117], v[250:251] op_sel_hi:[1,0]
	v_rcp_f32_e32 v114, v114
	v_rcp_f32_e32 v115, v115
	v_rcp_f32_e32 v116, v116
	v_rcp_f32_e32 v117, v117
	v_pk_mul_f32 v[114:115], v[106:107], v[114:115]
	v_pk_mul_f32 v[116:117], v[108:109], v[116:117]
	v_pk_mul_f32 v[114:115], v[110:111], v[114:115]
	v_pk_mul_f32 v[116:117], v[112:113], v[116:117]
; __device__ __forceinline__ unsigned cvt_pk_bf16(float lo, float hi) { unsigned r; asm volatile("v_cvt_pk_bf16_f32 %0, %1, %2" : "=v"(r) : "v"(lo), "v"(hi)); return r; }
; __device__ __forceinline__ f32x4 gelu4(f32x4 v) { return (f32x4){gelu_t(v[0]), gelu_t(v[1]), gelu_t(v[2]), gelu_t(v[3])}; }
; template <int CTRL> __device__ __forceinline__ f32x4 dpp4(f32x4 v) { return (f32x4){dpp_f<CTRL>(v[0]), dpp_f<CTRL>(v[1]), dpp_f<CTRL>(v[2]), dpp_f<CTRL>(v[3])}; }
;     __device__ __forceinline__ void operator()(const f32x4 (&acc)[2][2][4][2], const Unit& u, int wr, int wc, int fr, int fq) const {
;     ...
;                 const f32x4 wg0 = *(const f32x4*)(bias + c), wg1 = *(const f32x4*)(bias + NUPc + c), wg2 = *(const f32x4*)(bias + 2 * NUPc + c), bg = *(const f32x4*)(xin + c);
;                 const f32x4 wv0 = *(const f32x4*)(bias + DFFc + c), wv1 = *(const f32x4*)(bias + NUPc + DFFc + c), wv2 = *(const f32x4*)(bias + 2 * NUPc + DFFc + c), bv = *(const f32x4*)(xin + DFFc + c);
;     ...
;                     for (int m = 0; m < 4; ++m) {
;                         const f32x4 g = acc[ai][0][m][n] * rs[ai][m], v = acc[ai][1][m][n] * rs[ai][m];
;                         const f32x4 g1 = dpp4<0x121>(g), g2 = dpp4<0x122>(g), v1 = dpp4<0x121>(v), v2 = dpp4<0x122>(v);
;                         const f32x4 gp1 = (fr >= 1) ? g1 : pg1, gp2 = (fr >= 2) ? g2 : pg2, vp1 = (fr >= 1) ? v1 : pv1, vp2 = (fr >= 2) ? v2 : pv2;
;                         const f32x4 cgt = bg + wg0 * g + wg1 * gp1 + wg2 * gp2, cvl = bv + wv0 * v + wv1 * vp1 + wv2 * vp2;
;                         const f32x4 o = gelu4(cgt) * cvl;
;                         typedef unsigned u32x2e __attribute__((ext_vector_type(2)));
;                         u32x2e w; w.x = cvt_pk_bf16(o[0], o[1]); w.y = cvt_pk_bf16(o[2], o[3]);
;                         if (!(m == 0 && fr < 2)) *(u32x2e*)((bf16_t*)O + (size_t)(row0 + ai * HALF + m * 16) * DFFc + c) = w;
;                         pg1 = g1; pg2 = g2; pv1 = v1; pv2 = v2;
	v_cvt_pk_bf16_f32 v114, v114, v115
	v_cvt_pk_bf16_f32 v115, v116, v117
	v_mov_b32_e32 v187, v114
	v_mov_b32_e32 v189, v115
	v_pk_mul_f32 v[102:103], v[102:103], v[184:185] op_sel_hi:[1,0]
	v_pk_mul_f32 v[104:105], v[104:105], v[184:185] op_sel_hi:[1,0]
	v_pk_mul_f32 v[98:99], v[98:99], v[184:185] op_sel_hi:[1,0]
	v_pk_mul_f32 v[100:101], v[100:101], v[184:185] op_sel_hi:[1,0]
	v_pk_fma_f32 v[118:119], v[102:103], v[218:219], v[222:223]
	v_pk_fma_f32 v[120:121], v[104:105], v[220:221], v[224:225]
	v_pk_fma_f32 v[122:123], v[98:99], v[234:235], v[238:239]
	v_pk_fma_f32 v[124:125], v[100:101], v[236:237], v[240:241]
	v_fmac_f32_dpp v118, v102, v226 row_shr:1 row_mask:0xf bank_mask:0xf
	v_fmac_f32_dpp v119, v103, v227 row_shr:1 row_mask:0xf bank_mask:0xf
	v_fmac_f32_dpp v120, v104, v228 row_shr:1 row_mask:0xf bank_mask:0xf
	v_fmac_f32_dpp v121, v105, v229 row_shr:1 row_mask:0xf bank_mask:0xf
	v_fmac_f32_dpp v122, v98, v242 row_shr:1 row_mask:0xf bank_mask:0xf
	v_fmac_f32_dpp v123, v99, v243 row_shr:1 row_mask:0xf bank_mask:0xf
	v_fmac_f32_dpp v124, v100, v244 row_shr:1 row_mask:0xf bank_mask:0xf
	v_fmac_f32_dpp v125, v101, v245 row_shr:1 row_mask:0xf bank_mask:0xf
	v_fmac_f32_dpp v118, v102, v230 row_shr:2 row_mask:0xf bank_mask:0xf
	v_fmac_f32_dpp v119, v103, v231 row_shr:2 row_mask:0xf bank_mask:0xf
	v_fmac_f32_dpp v120, v104, v232 row_shr:2 row_mask:0xf bank_mask:0xf
	v_fmac_f32_dpp v121, v105, v233 row_shr:2 row_mask:0xf bank_mask:0xf
	v_fmac_f32_dpp v122, v98, v246 row_shr:2 row_mask:0xf bank_mask:0xf
	v_fmac_f32_dpp v123, v99, v247 row_shr:2 row_mask:0xf bank_mask:0xf
	v_fmac_f32_dpp v124, v100, v248 row_shr:2 row_mask:0xf bank_mask:0xf
	v_fmac_f32_dpp v125, v101, v249 row_shr:2 row_mask:0xf bank_mask:0xf
	v_fmac_f32_dpp v118, v142, v226 row_shl:15 row_mask:0xf bank_mask:0xf
	v_fmac_f32_dpp v119, v143, v227 row_shl:15 row_mask:0xf bank_mask:0xf
	v_fmac_f32_dpp v120, v144, v228 row_shl:15 row_mask:0xf bank_mask:0xf
	v_fmac_f32_dpp v121, v145, v229 row_shl:15 row_mask:0xf bank_mask:0xf
	v_fmac_f32_dpp v122, v138, v242 row_shl:15 row_mask:0xf bank_mask:0xf
	v_fmac_f32_dpp v123, v139, v243 row_shl:15 row_mask:0xf bank_mask:0xf
	v_fmac_f32_dpp v124, v140, v244 row_shl:15 row_mask:0xf bank_mask:0xf
	v_fmac_f32_dpp v125, v141, v245 row_shl:15 row_mask:0xf bank_mask:0xf
	v_fmac_f32_dpp v118, v142, v230 row_shl:14 row_mask:0xf bank_mask:0xf
	v_fmac_f32_dpp v119, v143, v231 row_shl:14 row_mask:0xf bank_mask:0xf
	v_fmac_f32_dpp v120, v144, v232 row_shl:14 row_mask:0xf bank_mask:0xf
	v_fmac_f32_dpp v121, v145, v233 row_shl:14 row_mask:0xf bank_mask:0xf
	v_fmac_f32_dpp v122, v138, v246 row_shl:14 row_mask:0xf bank_mask:0xf
	v_fmac_f32_dpp v123, v139, v247 row_shl:14 row_mask:0xf bank_mask:0xf
	v_fmac_f32_dpp v124, v140, v248 row_shl:14 row_mask:0xf bank_mask:0xf
	v_fmac_f32_dpp v125, v141, v249 row_shl:14 row_mask:0xf bank_mask:0xf
	v_pk_mul_f32 v[126:127], v[118:119], v[118:119]
	v_pk_mul_f32 v[128:129], v[120:121], v[120:121]
	v_pk_fma_f32 v[126:127], v[126:127], v[132:133], v[196:197] op_sel_hi:[1,0,0]
	v_pk_fma_f32 v[128:129], v[128:129], v[132:133], v[196:197] op_sel_hi:[1,0,0]
	v_pk_mul_f32 v[126:127], v[118:119], v[126:127]
	v_pk_mul_f32 v[128:129], v[120:121], v[128:129]
	v_exp_f32_e32 v126, v126
	v_exp_f32_e32 v127, v127
	v_exp_f32_e32 v128, v128
	v_exp_f32_e32 v129, v129
	v_pk_add_f32 v[126:127], v[126:127], v[250:251] op_sel_hi:[1,0]
	v_pk_add_f32 v[128:129], v[128:129], v[250:251] op_sel_hi:[1,0]
	v_rcp_f32_e32 v126, v126
	v_rcp_f32_e32 v127, v127
	v_rcp_f32_e32 v128, v128
	v_rcp_f32_e32 v129, v129
	v_pk_mul_f32 v[126:127], v[118:119], v[126:127]
	v_pk_mul_f32 v[128:129], v[120:121], v[128:129]
	v_pk_mul_f32 v[126:127], v[122:123], v[126:127]
	v_pk_mul_f32 v[128:129], v[124:125], v[128:129]
	v_cvt_pk_bf16_f32 v126, v126, v127
	v_cvt_pk_bf16_f32 v127, v128, v129
	v_mov_b32_e32 v191, v126
	v_mov_b32_e32 v193, v127
	global_load_dwordx4 v[154:157], v205, s[18:19] offset:16
	global_load_dwordx4 v[150:153], v205, s[20:21] offset:16
	global_load_dwordx4 v[142:145], v205, s[26:27] offset:16
	global_load_dwordx4 v[102:105], v205, s[28:29] offset:16
	global_load_dwordx4 v[134:137], v205, s[30:31] offset:16
	global_load_dwordx4 v[146:149], v205, s[38:39] offset:16
	global_load_dwordx4 v[138:141], v205, s[34:35] offset:16
	global_load_dwordx4 v[98:101], v205, s[36:37] offset:16
	v_pk_mul_f32 v[94:95], v[94:95], v[182:183] op_sel_hi:[1,0]
	v_pk_mul_f32 v[96:97], v[96:97], v[182:183] op_sel_hi:[1,0]
	v_pk_mul_f32 v[90:91], v[90:91], v[182:183] op_sel_hi:[1,0]
	v_pk_mul_f32 v[92:93], v[92:93], v[182:183] op_sel_hi:[1,0]
	v_pk_fma_f32 v[106:107], v[94:95], v[218:219], v[222:223]
	v_pk_fma_f32 v[108:109], v[96:97], v[220:221], v[224:225]
	v_pk_fma_f32 v[110:111], v[90:91], v[234:235], v[238:239]
	v_pk_fma_f32 v[112:113], v[92:93], v[236:237], v[240:241]
	v_fmac_f32_dpp v106, v94, v226 row_shr:1 row_mask:0xf bank_mask:0xf
	v_fmac_f32_dpp v107, v95, v227 row_shr:1 row_mask:0xf bank_mask:0xf
	v_fmac_f32_dpp v108, v96, v228 row_shr:1 row_mask:0xf bank_mask:0xf
	v_fmac_f32_dpp v109, v97, v229 row_shr:1 row_mask:0xf bank_mask:0xf
	v_fmac_f32_dpp v110, v90, v242 row_shr:1 row_mask:0xf bank_mask:0xf
	v_fmac_f32_dpp v111, v91, v243 row_shr:1 row_mask:0xf bank_mask:0xf
	v_fmac_f32_dpp v112, v92, v244 row_shr:1 row_mask:0xf bank_mask:0xf
	v_fmac_f32_dpp v113, v93, v245 row_shr:1 row_mask:0xf bank_mask:0xf
	v_fmac_f32_dpp v106, v94, v230 row_shr:2 row_mask:0xf bank_mask:0xf
	v_fmac_f32_dpp v107, v95, v231 row_shr:2 row_mask:0xf bank_mask:0xf
	v_fmac_f32_dpp v108, v96, v232 row_shr:2 row_mask:0xf bank_mask:0xf
	v_fmac_f32_dpp v109, v97, v233 row_shr:2 row_mask:0xf bank_mask:0xf
; __device__ __forceinline__ unsigned cvt_pk_bf16(float lo, float hi) { unsigned r; asm volatile("v_cvt_pk_bf16_f32 %0, %1, %2" : "=v"(r) : "v"(lo), "v"(hi)); return r; }
; __device__ __forceinline__ f32x4 gelu4(f32x4 v) { return (f32x4){gelu_t(v[0]), gelu_t(v[1]), gelu_t(v[2]), gelu_t(v[3])}; }
; template <int CTRL> __device__ __forceinline__ f32x4 dpp4(f32x4 v) { return (f32x4){dpp_f<CTRL>(v[0]), dpp_f<CTRL>(v[1]), dpp_f<CTRL>(v[2]), dpp_f<CTRL>(v[3])}; }
;     __device__ __forceinline__ void operator()(const f32x4 (&acc)[2][2][4][2], const Unit& u, int wr, int wc, int fr, int fq) const {
;     ...
;                     for (int m = 0; m < 4; ++m) {
;                         const f32x4 g = acc[ai][0][m][n] * rs[ai][m], v = acc[ai][1][m][n] * rs[ai][m];
;                         const f32x4 g1 = dpp4<0x121>(g), g2 = dpp4<0x122>(g), v1 = dpp4<0x121>(v), v2 = dpp4<0x122>(v);
;                         const f32x4 gp1 = (fr >= 1) ? g1 : pg1, gp2 = (fr >= 2) ? g2 : pg2, vp1 = (fr >= 1) ? v1 : pv1, vp2 = (fr >= 2) ? v2 : pv2;
;                         const f32x4 cgt = bg + wg0 * g + wg1 * gp1 + wg2 * gp2, cvl = bv + wv0 * v + wv1 * vp1 + wv2 * vp2;
;                         const f32x4 o = gelu4(cgt) * cvl;
;                         typedef unsigned u32x2e __attribute__((ext_vector_type(2)));
;                         u32x2e w; w.x = cvt_pk_bf16(o[0], o[1]); w.y = cvt_pk_bf16(o[2], o[3]);
;                         if (!(m == 0 && fr < 2)) *(u32x2e*)((bf16_t*)O + (size_t)(row0 + ai * HALF + m * 16) * DFFc + c) = w;
;                         pg1 = g1; pg2 = g2; pv1 = v1; pv2 = v2;
	v_fmac_f32_dpp v110, v90, v246 row_shr:2 row_mask:0xf bank_mask:0xf
	v_fmac_f32_dpp v111, v91, v247 row_shr:2 row_mask:0xf bank_mask:0xf
	v_fmac_f32_dpp v112, v92, v248 row_shr:2 row_mask:0xf bank_mask:0xf
	v_fmac_f32_dpp v113, v93, v249 row_shr:2 row_mask:0xf bank_mask:0xf
	v_pk_mul_f32 v[114:115], v[106:107], v[106:107]
	v_pk_mul_f32 v[116:117], v[108:109], v[108:109]
	v_pk_fma_f32 v[114:115], v[114:115], v[132:133], v[196:197] op_sel_hi:[1,0,0]
	v_pk_fma_f32 v[116:117], v[116:117], v[132:133], v[196:197] op_sel_hi:[1,0,0]
	v_pk_mul_f32 v[114:115], v[106:107], v[114:115]
	v_pk_mul_f32 v[116:117], v[108:109], v[116:117]
	v_exp_f32_e32 v114, v114
	v_exp_f32_e32 v115, v115
	v_exp_f32_e32 v116, v116
	v_exp_f32_e32 v117, v117
	v_pk_add_f32 v[114:115], v[114:115], v[250:251] op_sel_hi:[1,0]
	v_pk_add_f32 v[116:117], v[116:117], v[250:251] op_sel_hi:[1,0]
	v_rcp_f32_e32 v114, v114
	v_rcp_f32_e32 v115, v115
	v_rcp_f32_e32 v116, v116
	v_rcp_f32_e32 v117, v117
	v_pk_mul_f32 v[114:115], v[106:107], v[114:115]
	v_pk_mul_f32 v[116:117], v[108:109], v[116:117]
	v_pk_mul_f32 v[114:115], v[110:111], v[114:115]
	v_pk_mul_f32 v[116:117], v[112:113], v[116:117]
	v_cvt_pk_bf16_f32 v114, v114, v115
	v_cvt_pk_bf16_f32 v115, v116, v117
	v_mov_b32_e32 v206, v114
	v_mov_b32_e32 v207, v115
	v_pk_mul_f32 v[86:87], v[86:87], v[180:181] op_sel_hi:[1,0]
	v_pk_mul_f32 v[88:89], v[88:89], v[180:181] op_sel_hi:[1,0]
	v_pk_mul_f32 v[82:83], v[82:83], v[180:181] op_sel_hi:[1,0]
	v_pk_mul_f32 v[84:85], v[84:85], v[180:181] op_sel_hi:[1,0]
	v_pk_fma_f32 v[118:119], v[86:87], v[218:219], v[222:223]
	v_pk_fma_f32 v[120:121], v[88:89], v[220:221], v[224:225]
	v_pk_fma_f32 v[122:123], v[82:83], v[234:235], v[238:239]
	v_pk_fma_f32 v[124:125], v[84:85], v[236:237], v[240:241]
	v_fmac_f32_dpp v118, v86, v226 row_shr:1 row_mask:0xf bank_mask:0xf
	v_fmac_f32_dpp v119, v87, v227 row_shr:1 row_mask:0xf bank_mask:0xf
	v_fmac_f32_dpp v120, v88, v228 row_shr:1 row_mask:0xf bank_mask:0xf
	v_fmac_f32_dpp v121, v89, v229 row_shr:1 row_mask:0xf bank_mask:0xf
	v_fmac_f32_dpp v122, v82, v242 row_shr:1 row_mask:0xf bank_mask:0xf
	v_fmac_f32_dpp v123, v83, v243 row_shr:1 row_mask:0xf bank_mask:0xf
	v_fmac_f32_dpp v124, v84, v244 row_shr:1 row_mask:0xf bank_mask:0xf
	v_fmac_f32_dpp v125, v85, v245 row_shr:1 row_mask:0xf bank_mask:0xf
	v_fmac_f32_dpp v118, v86, v230 row_shr:2 row_mask:0xf bank_mask:0xf
	v_fmac_f32_dpp v119, v87, v231 row_shr:2 row_mask:0xf bank_mask:0xf
	v_fmac_f32_dpp v120, v88, v232 row_shr:2 row_mask:0xf bank_mask:0xf
	v_fmac_f32_dpp v121, v89, v233 row_shr:2 row_mask:0xf bank_mask:0xf
	v_fmac_f32_dpp v122, v82, v246 row_shr:2 row_mask:0xf bank_mask:0xf
	v_fmac_f32_dpp v123, v83, v247 row_shr:2 row_mask:0xf bank_mask:0xf
	v_fmac_f32_dpp v124, v84, v248 row_shr:2 row_mask:0xf bank_mask:0xf
	v_fmac_f32_dpp v125, v85, v249 row_shr:2 row_mask:0xf bank_mask:0xf
	v_fmac_f32_dpp v118, v94, v226 row_shl:15 row_mask:0xf bank_mask:0xf
	v_fmac_f32_dpp v119, v95, v227 row_shl:15 row_mask:0xf bank_mask:0xf
	v_fmac_f32_dpp v120, v96, v228 row_shl:15 row_mask:0xf bank_mask:0xf
	v_fmac_f32_dpp v121, v97, v229 row_shl:15 row_mask:0xf bank_mask:0xf
	v_fmac_f32_dpp v122, v90, v242 row_shl:15 row_mask:0xf bank_mask:0xf
	v_fmac_f32_dpp v123, v91, v243 row_shl:15 row_mask:0xf bank_mask:0xf
	v_fmac_f32_dpp v124, v92, v244 row_shl:15 row_mask:0xf bank_mask:0xf
	v_fmac_f32_dpp v125, v93, v245 row_shl:15 row_mask:0xf bank_mask:0xf
	v_fmac_f32_dpp v118, v94, v230 row_shl:14 row_mask:0xf bank_mask:0xf
	v_fmac_f32_dpp v119, v95, v231 row_shl:14 row_mask:0xf bank_mask:0xf
	v_fmac_f32_dpp v120, v96, v232 row_shl:14 row_mask:0xf bank_mask:0xf
	v_fmac_f32_dpp v121, v97, v233 row_shl:14 row_mask:0xf bank_mask:0xf
	v_fmac_f32_dpp v122, v90, v246 row_shl:14 row_mask:0xf bank_mask:0xf
	v_fmac_f32_dpp v123, v91, v247 row_shl:14 row_mask:0xf bank_mask:0xf
	v_fmac_f32_dpp v124, v92, v248 row_shl:14 row_mask:0xf bank_mask:0xf
	v_fmac_f32_dpp v125, v93, v249 row_shl:14 row_mask:0xf bank_mask:0xf
	v_pk_mul_f32 v[126:127], v[118:119], v[118:119]
	v_pk_mul_f32 v[128:129], v[120:121], v[120:121]
	v_pk_fma_f32 v[126:127], v[126:127], v[132:133], v[196:197] op_sel_hi:[1,0,0]
	v_pk_fma_f32 v[128:129], v[128:129], v[132:133], v[196:197] op_sel_hi:[1,0,0]
	v_pk_mul_f32 v[126:127], v[118:119], v[126:127]
	v_pk_mul_f32 v[128:129], v[120:121], v[128:129]
	v_exp_f32_e32 v126, v126
	v_exp_f32_e32 v127, v127
	v_exp_f32_e32 v128, v128
	v_exp_f32_e32 v129, v129
	v_pk_add_f32 v[126:127], v[126:127], v[250:251] op_sel_hi:[1,0]
	v_pk_add_f32 v[128:129], v[128:129], v[250:251] op_sel_hi:[1,0]
	v_rcp_f32_e32 v126, v126
	v_rcp_f32_e32 v127, v127
	v_rcp_f32_e32 v128, v128
	v_rcp_f32_e32 v129, v129
	v_pk_mul_f32 v[126:127], v[118:119], v[126:127]
	v_pk_mul_f32 v[128:129], v[120:121], v[128:129]
	v_pk_mul_f32 v[126:127], v[122:123], v[126:127]
	v_pk_mul_f32 v[128:129], v[124:125], v[128:129]
	v_cvt_pk_bf16_f32 v126, v126, v127
	v_cvt_pk_bf16_f32 v127, v128, v129
	v_mov_b32_e32 v208, v126
	v_mov_b32_e32 v209, v127
	v_pk_mul_f32 v[78:79], v[78:79], v[200:201] op_sel_hi:[1,0]
	v_pk_mul_f32 v[80:81], v[80:81], v[200:201] op_sel_hi:[1,0]
	v_pk_mul_f32 v[74:75], v[74:75], v[200:201] op_sel_hi:[1,0]
	v_pk_mul_f32 v[76:77], v[76:77], v[200:201] op_sel_hi:[1,0]
	v_pk_fma_f32 v[106:107], v[78:79], v[218:219], v[222:223]
	v_pk_fma_f32 v[108:109], v[80:81], v[220:221], v[224:225]
	v_pk_fma_f32 v[110:111], v[74:75], v[234:235], v[238:239]
	v_pk_fma_f32 v[112:113], v[76:77], v[236:237], v[240:241]
	v_fmac_f32_dpp v106, v78, v226 row_shr:1 row_mask:0xf bank_mask:0xf
	v_fmac_f32_dpp v107, v79, v227 row_shr:1 row_mask:0xf bank_mask:0xf
; __device__ __forceinline__ unsigned cvt_pk_bf16(float lo, float hi) { unsigned r; asm volatile("v_cvt_pk_bf16_f32 %0, %1, %2" : "=v"(r) : "v"(lo), "v"(hi)); return r; }
; __device__ __forceinline__ f32x4 gelu4(f32x4 v) { return (f32x4){gelu_t(v[0]), gelu_t(v[1]), gelu_t(v[2]), gelu_t(v[3])}; }
; template <int CTRL> __device__ __forceinline__ f32x4 dpp4(f32x4 v) { return (f32x4){dpp_f<CTRL>(v[0]), dpp_f<CTRL>(v[1]), dpp_f<CTRL>(v[2]), dpp_f<CTRL>(v[3])}; }
;     __device__ __forceinline__ void operator()(const f32x4 (&acc)[2][2][4][2], const Unit& u, int wr, int wc, int fr, int fq) const {
;     ...
;                     for (int m = 0; m < 4; ++m) {
;                         const f32x4 g = acc[ai][0][m][n] * rs[ai][m], v = acc[ai][1][m][n] * rs[ai][m];
;                         const f32x4 g1 = dpp4<0x121>(g), g2 = dpp4<0x122>(g), v1 = dpp4<0x121>(v), v2 = dpp4<0x122>(v);
;                         const f32x4 gp1 = (fr >= 1) ? g1 : pg1, gp2 = (fr >= 2) ? g2 : pg2, vp1 = (fr >= 1) ? v1 : pv1, vp2 = (fr >= 2) ? v2 : pv2;
;                         const f32x4 cgt = bg + wg0 * g + wg1 * gp1 + wg2 * gp2, cvl = bv + wv0 * v + wv1 * vp1 + wv2 * vp2;
;                         const f32x4 o = gelu4(cgt) * cvl;
;                         typedef unsigned u32x2e __attribute__((ext_vector_type(2)));
;                         u32x2e w; w.x = cvt_pk_bf16(o[0], o[1]); w.y = cvt_pk_bf16(o[2], o[3]);
;                         if (!(m == 0 && fr < 2)) *(u32x2e*)((bf16_t*)O + (size_t)(row0 + ai * HALF + m * 16) * DFFc + c) = w;
;                         pg1 = g1; pg2 = g2; pv1 = v1; pv2 = v2;
	v_fmac_f32_dpp v108, v80, v228 row_shr:1 row_mask:0xf bank_mask:0xf
	v_fmac_f32_dpp v109, v81, v229 row_shr:1 row_mask:0xf bank_mask:0xf
	v_fmac_f32_dpp v110, v74, v242 row_shr:1 row_mask:0xf bank_mask:0xf
	v_fmac_f32_dpp v111, v75, v243 row_shr:1 row_mask:0xf bank_mask:0xf
	v_fmac_f32_dpp v112, v76, v244 row_shr:1 row_mask:0xf bank_mask:0xf
	v_fmac_f32_dpp v113, v77, v245 row_shr:1 row_mask:0xf bank_mask:0xf
	v_fmac_f32_dpp v106, v78, v230 row_shr:2 row_mask:0xf bank_mask:0xf
	v_fmac_f32_dpp v107, v79, v231 row_shr:2 row_mask:0xf bank_mask:0xf
	v_fmac_f32_dpp v108, v80, v232 row_shr:2 row_mask:0xf bank_mask:0xf
	v_fmac_f32_dpp v109, v81, v233 row_shr:2 row_mask:0xf bank_mask:0xf
	v_fmac_f32_dpp v110, v74, v246 row_shr:2 row_mask:0xf bank_mask:0xf
	v_fmac_f32_dpp v111, v75, v247 row_shr:2 row_mask:0xf bank_mask:0xf
	v_fmac_f32_dpp v112, v76, v248 row_shr:2 row_mask:0xf bank_mask:0xf
	v_fmac_f32_dpp v113, v77, v249 row_shr:2 row_mask:0xf bank_mask:0xf
	v_fmac_f32_dpp v106, v86, v226 row_shl:15 row_mask:0xf bank_mask:0xf
	v_fmac_f32_dpp v107, v87, v227 row_shl:15 row_mask:0xf bank_mask:0xf
	v_fmac_f32_dpp v108, v88, v228 row_shl:15 row_mask:0xf bank_mask:0xf
	v_fmac_f32_dpp v109, v89, v229 row_shl:15 row_mask:0xf bank_mask:0xf
	v_fmac_f32_dpp v110, v82, v242 row_shl:15 row_mask:0xf bank_mask:0xf
	v_fmac_f32_dpp v111, v83, v243 row_shl:15 row_mask:0xf bank_mask:0xf
	v_fmac_f32_dpp v112, v84, v244 row_shl:15 row_mask:0xf bank_mask:0xf
	v_fmac_f32_dpp v113, v85, v245 row_shl:15 row_mask:0xf bank_mask:0xf
	v_fmac_f32_dpp v106, v86, v230 row_shl:14 row_mask:0xf bank_mask:0xf
	v_fmac_f32_dpp v107, v87, v231 row_shl:14 row_mask:0xf bank_mask:0xf
	v_fmac_f32_dpp v108, v88, v232 row_shl:14 row_mask:0xf bank_mask:0xf
	v_fmac_f32_dpp v109, v89, v233 row_shl:14 row_mask:0xf bank_mask:0xf
	v_fmac_f32_dpp v110, v82, v246 row_shl:14 row_mask:0xf bank_mask:0xf
	v_fmac_f32_dpp v111, v83, v247 row_shl:14 row_mask:0xf bank_mask:0xf
	v_fmac_f32_dpp v112, v84, v248 row_shl:14 row_mask:0xf bank_mask:0xf
	v_fmac_f32_dpp v113, v85, v249 row_shl:14 row_mask:0xf bank_mask:0xf
	v_pk_mul_f32 v[114:115], v[106:107], v[106:107]
	v_pk_mul_f32 v[116:117], v[108:109], v[108:109]
	v_pk_fma_f32 v[114:115], v[114:115], v[132:133], v[196:197] op_sel_hi:[1,0,0]
	v_pk_fma_f32 v[116:117], v[116:117], v[132:133], v[196:197] op_sel_hi:[1,0,0]
	v_pk_mul_f32 v[114:115], v[106:107], v[114:115]
	v_pk_mul_f32 v[116:117], v[108:109], v[116:117]
	v_exp_f32_e32 v114, v114
	v_exp_f32_e32 v115, v115
	v_exp_f32_e32 v116, v116
	v_exp_f32_e32 v117, v117
	v_pk_add_f32 v[114:115], v[114:115], v[250:251] op_sel_hi:[1,0]
	v_pk_add_f32 v[116:117], v[116:117], v[250:251] op_sel_hi:[1,0]
	v_rcp_f32_e32 v114, v114
	v_rcp_f32_e32 v115, v115
	v_rcp_f32_e32 v116, v116
	v_rcp_f32_e32 v117, v117
	v_pk_mul_f32 v[114:115], v[106:107], v[114:115]
	v_pk_mul_f32 v[116:117], v[108:109], v[116:117]
	v_pk_mul_f32 v[114:115], v[110:111], v[114:115]
	v_pk_mul_f32 v[116:117], v[112:113], v[116:117]
	v_cvt_pk_bf16_f32 v114, v114, v115
	v_cvt_pk_bf16_f32 v115, v116, v117
	v_mov_b32_e32 v210, v114
	v_mov_b32_e32 v211, v115
	v_pk_mul_f32 v[70:71], v[70:71], v[178:179] op_sel_hi:[1,0]
	v_pk_mul_f32 v[72:73], v[72:73], v[178:179] op_sel_hi:[1,0]
	v_pk_mul_f32 v[66:67], v[66:67], v[178:179] op_sel_hi:[1,0]
	v_pk_mul_f32 v[68:69], v[68:69], v[178:179] op_sel_hi:[1,0]
	v_pk_fma_f32 v[118:119], v[70:71], v[218:219], v[222:223]
	v_pk_fma_f32 v[120:121], v[72:73], v[220:221], v[224:225]
	v_pk_fma_f32 v[122:123], v[66:67], v[234:235], v[238:239]
	v_pk_fma_f32 v[124:125], v[68:69], v[236:237], v[240:241]
	v_fmac_f32_dpp v118, v70, v226 row_shr:1 row_mask:0xf bank_mask:0xf
	v_fmac_f32_dpp v119, v71, v227 row_shr:1 row_mask:0xf bank_mask:0xf
	v_fmac_f32_dpp v120, v72, v228 row_shr:1 row_mask:0xf bank_mask:0xf
	v_fmac_f32_dpp v121, v73, v229 row_shr:1 row_mask:0xf bank_mask:0xf
	v_fmac_f32_dpp v122, v66, v242 row_shr:1 row_mask:0xf bank_mask:0xf
	v_fmac_f32_dpp v123, v67, v243 row_shr:1 row_mask:0xf bank_mask:0xf
	v_fmac_f32_dpp v124, v68, v244 row_shr:1 row_mask:0xf bank_mask:0xf
	v_fmac_f32_dpp v125, v69, v245 row_shr:1 row_mask:0xf bank_mask:0xf
	v_fmac_f32_dpp v118, v70, v230 row_shr:2 row_mask:0xf bank_mask:0xf
	v_fmac_f32_dpp v119, v71, v231 row_shr:2 row_mask:0xf bank_mask:0xf
	v_fmac_f32_dpp v120, v72, v232 row_shr:2 row_mask:0xf bank_mask:0xf
	v_fmac_f32_dpp v121, v73, v233 row_shr:2 row_mask:0xf bank_mask:0xf
	v_fmac_f32_dpp v122, v66, v246 row_shr:2 row_mask:0xf bank_mask:0xf
	v_fmac_f32_dpp v123, v67, v247 row_shr:2 row_mask:0xf bank_mask:0xf
	v_fmac_f32_dpp v124, v68, v248 row_shr:2 row_mask:0xf bank_mask:0xf
	v_fmac_f32_dpp v125, v69, v249 row_shr:2 row_mask:0xf bank_mask:0xf
	v_fmac_f32_dpp v118, v78, v226 row_shl:15 row_mask:0xf bank_mask:0xf
	v_fmac_f32_dpp v119, v79, v227 row_shl:15 row_mask:0xf bank_mask:0xf
	v_fmac_f32_dpp v120, v80, v228 row_shl:15 row_mask:0xf bank_mask:0xf
	v_fmac_f32_dpp v121, v81, v229 row_shl:15 row_mask:0xf bank_mask:0xf
	v_fmac_f32_dpp v122, v74, v242 row_shl:15 row_mask:0xf bank_mask:0xf
	v_fmac_f32_dpp v123, v75, v243 row_shl:15 row_mask:0xf bank_mask:0xf
	v_fmac_f32_dpp v124, v76, v244 row_shl:15 row_mask:0xf bank_mask:0xf
	v_fmac_f32_dpp v125, v77, v245 row_shl:15 row_mask:0xf bank_mask:0xf
	v_fmac_f32_dpp v118, v78, v230 row_shl:14 row_mask:0xf bank_mask:0xf
	v_fmac_f32_dpp v119, v79, v231 row_shl:14 row_mask:0xf bank_mask:0xf
	v_fmac_f32_dpp v120, v80, v232 row_shl:14 row_mask:0xf bank_mask:0xf
	v_fmac_f32_dpp v121, v81, v233 row_shl:14 row_mask:0xf bank_mask:0xf
	v_fmac_f32_dpp v122, v74, v246 row_shl:14 row_mask:0xf bank_mask:0xf
	v_fmac_f32_dpp v123, v75, v247 row_shl:14 row_mask:0xf bank_mask:0xf
	v_fmac_f32_dpp v124, v76, v248 row_shl:14 row_mask:0xf bank_mask:0xf
	v_fmac_f32_dpp v125, v77, v249 row_shl:14 row_mask:0xf bank_mask:0xf
	v_pk_mul_f32 v[126:127], v[118:119], v[118:119]
	v_pk_mul_f32 v[128:129], v[120:121], v[120:121]
	v_pk_fma_f32 v[126:127], v[126:127], v[132:133], v[196:197] op_sel_hi:[1,0,0]
	v_pk_fma_f32 v[128:129], v[128:129], v[132:133], v[196:197] op_sel_hi:[1,0,0]
	v_pk_mul_f32 v[126:127], v[118:119], v[126:127]
	v_pk_mul_f32 v[128:129], v[120:121], v[128:129]
	v_exp_f32_e32 v126, v126
	v_exp_f32_e32 v127, v127
	v_exp_f32_e32 v128, v128
	v_exp_f32_e32 v129, v129
	v_pk_add_f32 v[126:127], v[126:127], v[250:251] op_sel_hi:[1,0]
	v_pk_add_f32 v[128:129], v[128:129], v[250:251] op_sel_hi:[1,0]
	v_rcp_f32_e32 v126, v126
	v_rcp_f32_e32 v127, v127
	v_rcp_f32_e32 v128, v128
	v_rcp_f32_e32 v129, v129
	v_pk_mul_f32 v[126:127], v[118:119], v[126:127]
	v_pk_mul_f32 v[128:129], v[120:121], v[128:129]
	v_pk_mul_f32 v[126:127], v[122:123], v[126:127]
	v_pk_mul_f32 v[128:129], v[124:125], v[128:129]
	v_cvt_pk_bf16_f32 v126, v126, v127
	v_cvt_pk_bf16_f32 v127, v128, v129
	v_mov_b32_e32 v133, v126
	v_mov_b32_e32 v251, v127
	s_waitcnt vmcnt(0)
; __device__ __forceinline__ unsigned cvt_pk_bf16(float lo, float hi) { unsigned r; asm volatile("v_cvt_pk_bf16_f32 %0, %1, %2" : "=v"(r) : "v"(lo), "v"(hi)); return r; }
; __device__ __forceinline__ f32x4 gelu4(f32x4 v) { return (f32x4){gelu_t(v[0]), gelu_t(v[1]), gelu_t(v[2]), gelu_t(v[3])}; }
; template <int CTRL> __device__ __forceinline__ f32x4 dpp4(f32x4 v) { return (f32x4){dpp_f<CTRL>(v[0]), dpp_f<CTRL>(v[1]), dpp_f<CTRL>(v[2]), dpp_f<CTRL>(v[3])}; }
;     __device__ __forceinline__ void operator()(const f32x4 (&acc)[2][2][4][2], const Unit& u, int wr, int wc, int fr, int fq) const {
;     ...
;                     for (int m = 0; m < 4; ++m) {
;                         const f32x4 g = acc[ai][0][m][n] * rs[ai][m], v = acc[ai][1][m][n] * rs[ai][m];
;                         const f32x4 g1 = dpp4<0x121>(g), g2 = dpp4<0x122>(g), v1 = dpp4<0x121>(v), v2 = dpp4<0x122>(v);
;                         const f32x4 gp1 = (fr >= 1) ? g1 : pg1, gp2 = (fr >= 2) ? g2 : pg2, vp1 = (fr >= 1) ? v1 : pv1, vp2 = (fr >= 2) ? v2 : pv2;
;                         const f32x4 cgt = bg + wg0 * g + wg1 * gp1 + wg2 * gp2, cvl = bv + wv0 * v + wv1 * vp1 + wv2 * vp2;
;                         const f32x4 o = gelu4(cgt) * cvl;
;                         typedef unsigned u32x2e __attribute__((ext_vector_type(2)));
;                         u32x2e w; w.x = cvt_pk_bf16(o[0], o[1]); w.y = cvt_pk_bf16(o[2], o[3]);
;                         if (!(m == 0 && fr < 2)) *(u32x2e*)((bf16_t*)O + (size_t)(row0 + ai * HALF + m * 16) * DFFc + c) = w;
;                         pg1 = g1; pg2 = g2; pv1 = v1; pv2 = v2;
	v_pk_mul_f32 v[62:63], v[62:63], v[188:189] op_sel_hi:[1,0]
	v_pk_mul_f32 v[64:65], v[64:65], v[188:189] op_sel_hi:[1,0]
	v_pk_mul_f32 v[58:59], v[58:59], v[188:189] op_sel_hi:[1,0]
	v_pk_mul_f32 v[60:61], v[60:61], v[188:189] op_sel_hi:[1,0]
	v_pk_fma_f32 v[106:107], v[62:63], v[154:155], v[150:151]
	v_pk_fma_f32 v[108:109], v[64:65], v[156:157], v[152:153]
	v_pk_fma_f32 v[110:111], v[58:59], v[134:135], v[146:147]
	v_pk_fma_f32 v[112:113], v[60:61], v[136:137], v[148:149]
	v_fmac_f32_dpp v106, v62, v142 row_shr:1 row_mask:0xf bank_mask:0xf
	v_fmac_f32_dpp v107, v63, v143 row_shr:1 row_mask:0xf bank_mask:0xf
	v_fmac_f32_dpp v108, v64, v144 row_shr:1 row_mask:0xf bank_mask:0xf
	v_fmac_f32_dpp v109, v65, v145 row_shr:1 row_mask:0xf bank_mask:0xf
	v_fmac_f32_dpp v110, v58, v138 row_shr:1 row_mask:0xf bank_mask:0xf
	v_fmac_f32_dpp v111, v59, v139 row_shr:1 row_mask:0xf bank_mask:0xf
	v_fmac_f32_dpp v112, v60, v140 row_shr:1 row_mask:0xf bank_mask:0xf
	v_fmac_f32_dpp v113, v61, v141 row_shr:1 row_mask:0xf bank_mask:0xf
	v_fmac_f32_dpp v106, v62, v102 row_shr:2 row_mask:0xf bank_mask:0xf
	v_fmac_f32_dpp v107, v63, v103 row_shr:2 row_mask:0xf bank_mask:0xf
	v_fmac_f32_dpp v108, v64, v104 row_shr:2 row_mask:0xf bank_mask:0xf
	v_fmac_f32_dpp v109, v65, v105 row_shr:2 row_mask:0xf bank_mask:0xf
	v_fmac_f32_dpp v110, v58, v98 row_shr:2 row_mask:0xf bank_mask:0xf
	v_fmac_f32_dpp v111, v59, v99 row_shr:2 row_mask:0xf bank_mask:0xf
	v_fmac_f32_dpp v112, v60, v100 row_shr:2 row_mask:0xf bank_mask:0xf
	v_fmac_f32_dpp v113, v61, v101 row_shr:2 row_mask:0xf bank_mask:0xf
	v_pk_mul_f32 v[114:115], v[106:107], v[106:107]
	v_pk_mul_f32 v[116:117], v[108:109], v[108:109]
	v_pk_fma_f32 v[114:115], v[114:115], v[132:133], v[196:197] op_sel_hi:[1,0,0]
	v_pk_fma_f32 v[116:117], v[116:117], v[132:133], v[196:197] op_sel_hi:[1,0,0]
	v_pk_mul_f32 v[114:115], v[106:107], v[114:115]
	v_pk_mul_f32 v[116:117], v[108:109], v[116:117]
	v_exp_f32_e32 v114, v114
	v_exp_f32_e32 v115, v115
	v_exp_f32_e32 v116, v116
	v_exp_f32_e32 v117, v117
	v_pk_add_f32 v[114:115], v[114:115], v[250:251] op_sel_hi:[1,0]
	v_pk_add_f32 v[116:117], v[116:117], v[250:251] op_sel_hi:[1,0]
	v_rcp_f32_e32 v114, v114
	v_rcp_f32_e32 v115, v115
	v_rcp_f32_e32 v116, v116
	v_rcp_f32_e32 v117, v117
	v_pk_mul_f32 v[114:115], v[106:107], v[114:115]
	v_pk_mul_f32 v[116:117], v[108:109], v[116:117]
	v_pk_mul_f32 v[114:115], v[110:111], v[114:115]
	v_pk_mul_f32 v[116:117], v[112:113], v[116:117]
	v_cvt_pk_bf16_f32 v117, v116, v117
	v_cvt_pk_bf16_f32 v116, v114, v115
	v_mov_b32_e32 v114, v179
	v_mov_b32_e32 v115, v181
	s_and_saveexec_b64 s[48:49], s[10:11]
	global_store_dwordx4 v199, v[114:117], s[68:69]
	s_or_b64 exec, exec, s[48:49]
	v_pk_mul_f32 v[54:55], v[54:55], v[190:191] op_sel_hi:[1,0]
	v_pk_mul_f32 v[56:57], v[56:57], v[190:191] op_sel_hi:[1,0]
	v_pk_mul_f32 v[50:51], v[50:51], v[190:191] op_sel_hi:[1,0]
	v_pk_mul_f32 v[52:53], v[52:53], v[190:191] op_sel_hi:[1,0]
	v_pk_fma_f32 v[118:119], v[54:55], v[154:155], v[150:151]
	v_pk_fma_f32 v[120:121], v[56:57], v[156:157], v[152:153]
	v_pk_fma_f32 v[122:123], v[50:51], v[134:135], v[146:147]
	v_pk_fma_f32 v[124:125], v[52:53], v[136:137], v[148:149]
	v_fmac_f32_dpp v118, v54, v142 row_shr:1 row_mask:0xf bank_mask:0xf
	v_fmac_f32_dpp v119, v55, v143 row_shr:1 row_mask:0xf bank_mask:0xf
	v_fmac_f32_dpp v120, v56, v144 row_shr:1 row_mask:0xf bank_mask:0xf
	v_fmac_f32_dpp v121, v57, v145 row_shr:1 row_mask:0xf bank_mask:0xf
	v_fmac_f32_dpp v122, v50, v138 row_shr:1 row_mask:0xf bank_mask:0xf
	v_fmac_f32_dpp v123, v51, v139 row_shr:1 row_mask:0xf bank_mask:0xf
	v_fmac_f32_dpp v124, v52, v140 row_shr:1 row_mask:0xf bank_mask:0xf
	v_fmac_f32_dpp v125, v53, v141 row_shr:1 row_mask:0xf bank_mask:0xf
	v_fmac_f32_dpp v118, v54, v102 row_shr:2 row_mask:0xf bank_mask:0xf
	v_fmac_f32_dpp v119, v55, v103 row_shr:2 row_mask:0xf bank_mask:0xf
	v_fmac_f32_dpp v120, v56, v104 row_shr:2 row_mask:0xf bank_mask:0xf
	v_fmac_f32_dpp v121, v57, v105 row_shr:2 row_mask:0xf bank_mask:0xf
	v_fmac_f32_dpp v122, v50, v98 row_shr:2 row_mask:0xf bank_mask:0xf
	v_fmac_f32_dpp v123, v51, v99 row_shr:2 row_mask:0xf bank_mask:0xf
	v_fmac_f32_dpp v124, v52, v100 row_shr:2 row_mask:0xf bank_mask:0xf
	v_fmac_f32_dpp v125, v53, v101 row_shr:2 row_mask:0xf bank_mask:0xf
	v_fmac_f32_dpp v118, v62, v142 row_shl:15 row_mask:0xf bank_mask:0xf
	v_fmac_f32_dpp v119, v63, v143 row_shl:15 row_mask:0xf bank_mask:0xf
	v_fmac_f32_dpp v120, v64, v144 row_shl:15 row_mask:0xf bank_mask:0xf
	v_fmac_f32_dpp v121, v65, v145 row_shl:15 row_mask:0xf bank_mask:0xf
	v_fmac_f32_dpp v122, v58, v138 row_shl:15 row_mask:0xf bank_mask:0xf
	v_fmac_f32_dpp v123, v59, v139 row_shl:15 row_mask:0xf bank_mask:0xf
	v_fmac_f32_dpp v124, v60, v140 row_shl:15 row_mask:0xf bank_mask:0xf
	v_fmac_f32_dpp v125, v61, v141 row_shl:15 row_mask:0xf bank_mask:0xf
	v_fmac_f32_dpp v118, v62, v102 row_shl:14 row_mask:0xf bank_mask:0xf
	v_fmac_f32_dpp v119, v63, v103 row_shl:14 row_mask:0xf bank_mask:0xf
	v_fmac_f32_dpp v120, v64, v104 row_shl:14 row_mask:0xf bank_mask:0xf
	v_fmac_f32_dpp v121, v65, v105 row_shl:14 row_mask:0xf bank_mask:0xf
	v_fmac_f32_dpp v122, v58, v98 row_shl:14 row_mask:0xf bank_mask:0xf
	v_fmac_f32_dpp v123, v59, v99 row_shl:14 row_mask:0xf bank_mask:0xf
	v_fmac_f32_dpp v124, v60, v100 row_shl:14 row_mask:0xf bank_mask:0xf
	v_fmac_f32_dpp v125, v61, v101 row_shl:14 row_mask:0xf bank_mask:0xf
	v_pk_mul_f32 v[126:127], v[118:119], v[118:119]
	v_pk_mul_f32 v[128:129], v[120:121], v[120:121]
	v_pk_fma_f32 v[126:127], v[126:127], v[132:133], v[196:197] op_sel_hi:[1,0,0]
	v_pk_fma_f32 v[128:129], v[128:129], v[132:133], v[196:197] op_sel_hi:[1,0,0]
; __device__ __forceinline__ unsigned cvt_pk_bf16(float lo, float hi) { unsigned r; asm volatile("v_cvt_pk_bf16_f32 %0, %1, %2" : "=v"(r) : "v"(lo), "v"(hi)); return r; }
; __device__ __forceinline__ f32x4 gelu4(f32x4 v) { return (f32x4){gelu_t(v[0]), gelu_t(v[1]), gelu_t(v[2]), gelu_t(v[3])}; }
; template <int CTRL> __device__ __forceinline__ f32x4 dpp4(f32x4 v) { return (f32x4){dpp_f<CTRL>(v[0]), dpp_f<CTRL>(v[1]), dpp_f<CTRL>(v[2]), dpp_f<CTRL>(v[3])}; }
;     __device__ __forceinline__ void operator()(const f32x4 (&acc)[2][2][4][2], const Unit& u, int wr, int wc, int fr, int fq) const {
;     ...
;                     for (int m = 0; m < 4; ++m) {
;                         const f32x4 g = acc[ai][0][m][n] * rs[ai][m], v = acc[ai][1][m][n] * rs[ai][m];
;                         const f32x4 g1 = dpp4<0x121>(g), g2 = dpp4<0x122>(g), v1 = dpp4<0x121>(v), v2 = dpp4<0x122>(v);
;                         const f32x4 gp1 = (fr >= 1) ? g1 : pg1, gp2 = (fr >= 2) ? g2 : pg2, vp1 = (fr >= 1) ? v1 : pv1, vp2 = (fr >= 2) ? v2 : pv2;
;                         const f32x4 cgt = bg + wg0 * g + wg1 * gp1 + wg2 * gp2, cvl = bv + wv0 * v + wv1 * vp1 + wv2 * vp2;
;                         const f32x4 o = gelu4(cgt) * cvl;
;                         typedef unsigned u32x2e __attribute__((ext_vector_type(2)));
;                         u32x2e w; w.x = cvt_pk_bf16(o[0], o[1]); w.y = cvt_pk_bf16(o[2], o[3]);
;                         if (!(m == 0 && fr < 2)) *(u32x2e*)((bf16_t*)O + (size_t)(row0 + ai * HALF + m * 16) * DFFc + c) = w;
;                         pg1 = g1; pg2 = g2; pv1 = v1; pv2 = v2;
	v_pk_mul_f32 v[126:127], v[118:119], v[126:127]
	v_pk_mul_f32 v[128:129], v[120:121], v[128:129]
	v_exp_f32_e32 v126, v126
	v_exp_f32_e32 v127, v127
	v_exp_f32_e32 v128, v128
	v_exp_f32_e32 v129, v129
	v_pk_add_f32 v[126:127], v[126:127], v[250:251] op_sel_hi:[1,0]
	v_pk_add_f32 v[128:129], v[128:129], v[250:251] op_sel_hi:[1,0]
	v_rcp_f32_e32 v126, v126
	v_rcp_f32_e32 v127, v127
	v_rcp_f32_e32 v128, v128
	v_rcp_f32_e32 v129, v129
	v_pk_mul_f32 v[126:127], v[118:119], v[126:127]
	v_pk_mul_f32 v[128:129], v[120:121], v[128:129]
	v_pk_mul_f32 v[126:127], v[122:123], v[126:127]
	v_pk_mul_f32 v[128:129], v[124:125], v[128:129]
	v_cvt_pk_bf16_f32 v129, v128, v129
	v_cvt_pk_bf16_f32 v128, v126, v127
	v_add_u32_e32 v131, 0x2c000, v199
	v_mov_b32_e32 v126, v183
	v_mov_b32_e32 v127, v185
	global_store_dwordx4 v131, v[126:129], s[68:69]
	v_pk_mul_f32 v[46:47], v[46:47], v[192:193] op_sel_hi:[1,0]
	v_pk_mul_f32 v[48:49], v[48:49], v[192:193] op_sel_hi:[1,0]
	v_pk_mul_f32 v[42:43], v[42:43], v[192:193] op_sel_hi:[1,0]
	v_pk_mul_f32 v[44:45], v[44:45], v[192:193] op_sel_hi:[1,0]
	v_pk_fma_f32 v[106:107], v[46:47], v[154:155], v[150:151]
	v_pk_fma_f32 v[108:109], v[48:49], v[156:157], v[152:153]
	v_pk_fma_f32 v[110:111], v[42:43], v[134:135], v[146:147]
	v_pk_fma_f32 v[112:113], v[44:45], v[136:137], v[148:149]
	v_fmac_f32_dpp v106, v46, v142 row_shr:1 row_mask:0xf bank_mask:0xf
	v_fmac_f32_dpp v107, v47, v143 row_shr:1 row_mask:0xf bank_mask:0xf
	v_fmac_f32_dpp v108, v48, v144 row_shr:1 row_mask:0xf bank_mask:0xf
	v_fmac_f32_dpp v109, v49, v145 row_shr:1 row_mask:0xf bank_mask:0xf
	v_fmac_f32_dpp v110, v42, v138 row_shr:1 row_mask:0xf bank_mask:0xf
	v_fmac_f32_dpp v111, v43, v139 row_shr:1 row_mask:0xf bank_mask:0xf
	v_fmac_f32_dpp v112, v44, v140 row_shr:1 row_mask:0xf bank_mask:0xf
	v_fmac_f32_dpp v113, v45, v141 row_shr:1 row_mask:0xf bank_mask:0xf
	v_fmac_f32_dpp v106, v46, v102 row_shr:2 row_mask:0xf bank_mask:0xf
	v_fmac_f32_dpp v107, v47, v103 row_shr:2 row_mask:0xf bank_mask:0xf
	v_fmac_f32_dpp v108, v48, v104 row_shr:2 row_mask:0xf bank_mask:0xf
	v_fmac_f32_dpp v109, v49, v105 row_shr:2 row_mask:0xf bank_mask:0xf
	v_fmac_f32_dpp v110, v42, v98 row_shr:2 row_mask:0xf bank_mask:0xf
	v_fmac_f32_dpp v111, v43, v99 row_shr:2 row_mask:0xf bank_mask:0xf
	v_fmac_f32_dpp v112, v44, v100 row_shr:2 row_mask:0xf bank_mask:0xf
	v_fmac_f32_dpp v113, v45, v101 row_shr:2 row_mask:0xf bank_mask:0xf
	v_fmac_f32_dpp v106, v54, v142 row_shl:15 row_mask:0xf bank_mask:0xf
	v_fmac_f32_dpp v107, v55, v143 row_shl:15 row_mask:0xf bank_mask:0xf
	v_fmac_f32_dpp v108, v56, v144 row_shl:15 row_mask:0xf bank_mask:0xf
	v_fmac_f32_dpp v109, v57, v145 row_shl:15 row_mask:0xf bank_mask:0xf
	v_fmac_f32_dpp v110, v50, v138 row_shl:15 row_mask:0xf bank_mask:0xf
	v_fmac_f32_dpp v111, v51, v139 row_shl:15 row_mask:0xf bank_mask:0xf
	v_fmac_f32_dpp v112, v52, v140 row_shl:15 row_mask:0xf bank_mask:0xf
	v_fmac_f32_dpp v113, v53, v141 row_shl:15 row_mask:0xf bank_mask:0xf
	v_fmac_f32_dpp v106, v54, v102 row_shl:14 row_mask:0xf bank_mask:0xf
	v_fmac_f32_dpp v107, v55, v103 row_shl:14 row_mask:0xf bank_mask:0xf
	v_fmac_f32_dpp v108, v56, v104 row_shl:14 row_mask:0xf bank_mask:0xf
	v_fmac_f32_dpp v109, v57, v105 row_shl:14 row_mask:0xf bank_mask:0xf
	v_fmac_f32_dpp v110, v50, v98 row_shl:14 row_mask:0xf bank_mask:0xf
	v_fmac_f32_dpp v111, v51, v99 row_shl:14 row_mask:0xf bank_mask:0xf
	v_fmac_f32_dpp v112, v52, v100 row_shl:14 row_mask:0xf bank_mask:0xf
	v_fmac_f32_dpp v113, v53, v101 row_shl:14 row_mask:0xf bank_mask:0xf
	v_pk_mul_f32 v[114:115], v[106:107], v[106:107]
	v_pk_mul_f32 v[116:117], v[108:109], v[108:109]
	v_pk_fma_f32 v[114:115], v[114:115], v[132:133], v[196:197] op_sel_hi:[1,0,0]
	v_pk_fma_f32 v[116:117], v[116:117], v[132:133], v[196:197] op_sel_hi:[1,0,0]
	v_pk_mul_f32 v[114:115], v[106:107], v[114:115]
	v_pk_mul_f32 v[116:117], v[108:109], v[116:117]
	v_exp_f32_e32 v114, v114
	v_exp_f32_e32 v115, v115
	v_exp_f32_e32 v116, v116
	v_exp_f32_e32 v117, v117
	v_pk_add_f32 v[114:115], v[114:115], v[250:251] op_sel_hi:[1,0]
	v_pk_add_f32 v[116:117], v[116:117], v[250:251] op_sel_hi:[1,0]
	v_rcp_f32_e32 v114, v114
	v_rcp_f32_e32 v115, v115
	v_rcp_f32_e32 v116, v116
	v_rcp_f32_e32 v117, v117
	v_pk_mul_f32 v[114:115], v[106:107], v[114:115]
	v_pk_mul_f32 v[116:117], v[108:109], v[116:117]
	v_pk_mul_f32 v[114:115], v[110:111], v[114:115]
	v_pk_mul_f32 v[116:117], v[112:113], v[116:117]
	v_cvt_pk_bf16_f32 v117, v116, v117
	v_cvt_pk_bf16_f32 v116, v114, v115
	v_add_u32_e32 v130, 0x58000, v199
	v_mov_b32_e32 v114, v187
	v_mov_b32_e32 v115, v189
	global_store_dwordx4 v130, v[114:117], s[68:69]
	v_pk_mul_f32 v[38:39], v[38:39], v[184:185] op_sel_hi:[1,0]
	v_pk_mul_f32 v[40:41], v[40:41], v[184:185] op_sel_hi:[1,0]
	v_pk_mul_f32 v[34:35], v[34:35], v[184:185] op_sel_hi:[1,0]
	v_pk_mul_f32 v[36:37], v[36:37], v[184:185] op_sel_hi:[1,0]
	v_pk_fma_f32 v[118:119], v[38:39], v[154:155], v[150:151]
	v_pk_fma_f32 v[120:121], v[40:41], v[156:157], v[152:153]
	v_pk_fma_f32 v[122:123], v[34:35], v[134:135], v[146:147]
	v_pk_fma_f32 v[124:125], v[36:37], v[136:137], v[148:149]
	v_fmac_f32_dpp v118, v38, v142 row_shr:1 row_mask:0xf bank_mask:0xf
	v_fmac_f32_dpp v119, v39, v143 row_shr:1 row_mask:0xf bank_mask:0xf
	v_fmac_f32_dpp v120, v40, v144 row_shr:1 row_mask:0xf bank_mask:0xf
	v_fmac_f32_dpp v121, v41, v145 row_shr:1 row_mask:0xf bank_mask:0xf
	v_fmac_f32_dpp v122, v34, v138 row_shr:1 row_mask:0xf bank_mask:0xf
	v_fmac_f32_dpp v123, v35, v139 row_shr:1 row_mask:0xf bank_mask:0xf
	v_fmac_f32_dpp v124, v36, v140 row_shr:1 row_mask:0xf bank_mask:0xf
	v_fmac_f32_dpp v125, v37, v141 row_shr:1 row_mask:0xf bank_mask:0xf
; __device__ __forceinline__ unsigned cvt_pk_bf16(float lo, float hi) { unsigned r; asm volatile("v_cvt_pk_bf16_f32 %0, %1, %2" : "=v"(r) : "v"(lo), "v"(hi)); return r; }
; __device__ __forceinline__ f32x4 gelu4(f32x4 v) { return (f32x4){gelu_t(v[0]), gelu_t(v[1]), gelu_t(v[2]), gelu_t(v[3])}; }
; template <int CTRL> __device__ __forceinline__ f32x4 dpp4(f32x4 v) { return (f32x4){dpp_f<CTRL>(v[0]), dpp_f<CTRL>(v[1]), dpp_f<CTRL>(v[2]), dpp_f<CTRL>(v[3])}; }
;     __device__ __forceinline__ void operator()(const f32x4 (&acc)[2][2][4][2], const Unit& u, int wr, int wc, int fr, int fq) const {
;     ...
;                     for (int m = 0; m < 4; ++m) {
;                         const f32x4 g = acc[ai][0][m][n] * rs[ai][m], v = acc[ai][1][m][n] * rs[ai][m];
;                         const f32x4 g1 = dpp4<0x121>(g), g2 = dpp4<0x122>(g), v1 = dpp4<0x121>(v), v2 = dpp4<0x122>(v);
;                         const f32x4 gp1 = (fr >= 1) ? g1 : pg1, gp2 = (fr >= 2) ? g2 : pg2, vp1 = (fr >= 1) ? v1 : pv1, vp2 = (fr >= 2) ? v2 : pv2;
;                         const f32x4 cgt = bg + wg0 * g + wg1 * gp1 + wg2 * gp2, cvl = bv + wv0 * v + wv1 * vp1 + wv2 * vp2;
;                         const f32x4 o = gelu4(cgt) * cvl;
;                         typedef unsigned u32x2e __attribute__((ext_vector_type(2)));
;                         u32x2e w; w.x = cvt_pk_bf16(o[0], o[1]); w.y = cvt_pk_bf16(o[2], o[3]);
;                         if (!(m == 0 && fr < 2)) *(u32x2e*)((bf16_t*)O + (size_t)(row0 + ai * HALF + m * 16) * DFFc + c) = w;
;                         pg1 = g1; pg2 = g2; pv1 = v1; pv2 = v2;
	v_fmac_f32_dpp v118, v38, v102 row_shr:2 row_mask:0xf bank_mask:0xf
	v_fmac_f32_dpp v119, v39, v103 row_shr:2 row_mask:0xf bank_mask:0xf
	v_fmac_f32_dpp v120, v40, v104 row_shr:2 row_mask:0xf bank_mask:0xf
	v_fmac_f32_dpp v121, v41, v105 row_shr:2 row_mask:0xf bank_mask:0xf
	v_fmac_f32_dpp v122, v34, v98 row_shr:2 row_mask:0xf bank_mask:0xf
	v_fmac_f32_dpp v123, v35, v99 row_shr:2 row_mask:0xf bank_mask:0xf
	v_fmac_f32_dpp v124, v36, v100 row_shr:2 row_mask:0xf bank_mask:0xf
	v_fmac_f32_dpp v125, v37, v101 row_shr:2 row_mask:0xf bank_mask:0xf
	v_fmac_f32_dpp v118, v46, v142 row_shl:15 row_mask:0xf bank_mask:0xf
	v_fmac_f32_dpp v119, v47, v143 row_shl:15 row_mask:0xf bank_mask:0xf
	v_fmac_f32_dpp v120, v48, v144 row_shl:15 row_mask:0xf bank_mask:0xf
	v_fmac_f32_dpp v121, v49, v145 row_shl:15 row_mask:0xf bank_mask:0xf
	v_fmac_f32_dpp v122, v42, v138 row_shl:15 row_mask:0xf bank_mask:0xf
	v_fmac_f32_dpp v123, v43, v139 row_shl:15 row_mask:0xf bank_mask:0xf
	v_fmac_f32_dpp v124, v44, v140 row_shl:15 row_mask:0xf bank_mask:0xf
	v_fmac_f32_dpp v125, v45, v141 row_shl:15 row_mask:0xf bank_mask:0xf
	v_fmac_f32_dpp v118, v46, v102 row_shl:14 row_mask:0xf bank_mask:0xf
	v_fmac_f32_dpp v119, v47, v103 row_shl:14 row_mask:0xf bank_mask:0xf
	v_fmac_f32_dpp v120, v48, v104 row_shl:14 row_mask:0xf bank_mask:0xf
	v_fmac_f32_dpp v121, v49, v105 row_shl:14 row_mask:0xf bank_mask:0xf
	v_fmac_f32_dpp v122, v42, v98 row_shl:14 row_mask:0xf bank_mask:0xf
	v_fmac_f32_dpp v123, v43, v99 row_shl:14 row_mask:0xf bank_mask:0xf
	v_fmac_f32_dpp v124, v44, v100 row_shl:14 row_mask:0xf bank_mask:0xf
	v_fmac_f32_dpp v125, v45, v101 row_shl:14 row_mask:0xf bank_mask:0xf
	v_pk_mul_f32 v[126:127], v[118:119], v[118:119]
	v_pk_mul_f32 v[128:129], v[120:121], v[120:121]
	v_pk_fma_f32 v[126:127], v[126:127], v[132:133], v[196:197] op_sel_hi:[1,0,0]
	v_pk_fma_f32 v[128:129], v[128:129], v[132:133], v[196:197] op_sel_hi:[1,0,0]
	v_pk_mul_f32 v[126:127], v[118:119], v[126:127]
	v_pk_mul_f32 v[128:129], v[120:121], v[128:129]
	v_exp_f32_e32 v126, v126
	v_exp_f32_e32 v127, v127
	v_exp_f32_e32 v128, v128
	v_exp_f32_e32 v129, v129
	v_pk_add_f32 v[126:127], v[126:127], v[250:251] op_sel_hi:[1,0]
	v_pk_add_f32 v[128:129], v[128:129], v[250:251] op_sel_hi:[1,0]
	v_rcp_f32_e32 v126, v126
	v_rcp_f32_e32 v127, v127
	v_rcp_f32_e32 v128, v128
	v_rcp_f32_e32 v129, v129
	v_pk_mul_f32 v[126:127], v[118:119], v[126:127]
	v_pk_mul_f32 v[128:129], v[120:121], v[128:129]
	v_pk_mul_f32 v[126:127], v[122:123], v[126:127]
	v_pk_mul_f32 v[128:129], v[124:125], v[128:129]
	v_cvt_pk_bf16_f32 v129, v128, v129
	v_cvt_pk_bf16_f32 v128, v126, v127
	v_add_u32_e32 v131, 0x84000, v199
	v_mov_b32_e32 v126, v191
	v_mov_b32_e32 v127, v193
	global_store_dwordx4 v131, v[126:129], s[68:69]
	v_pk_mul_f32 v[30:31], v[30:31], v[182:183] op_sel_hi:[1,0]
	v_pk_mul_f32 v[32:33], v[32:33], v[182:183] op_sel_hi:[1,0]
	v_pk_mul_f32 v[26:27], v[26:27], v[182:183] op_sel_hi:[1,0]
	v_pk_mul_f32 v[28:29], v[28:29], v[182:183] op_sel_hi:[1,0]
	v_pk_fma_f32 v[106:107], v[30:31], v[154:155], v[150:151]
	v_pk_fma_f32 v[108:109], v[32:33], v[156:157], v[152:153]
	v_pk_fma_f32 v[110:111], v[26:27], v[134:135], v[146:147]
	v_pk_fma_f32 v[112:113], v[28:29], v[136:137], v[148:149]
	v_fmac_f32_dpp v106, v30, v142 row_shr:1 row_mask:0xf bank_mask:0xf
	v_fmac_f32_dpp v107, v31, v143 row_shr:1 row_mask:0xf bank_mask:0xf
	v_fmac_f32_dpp v108, v32, v144 row_shr:1 row_mask:0xf bank_mask:0xf
	v_fmac_f32_dpp v109, v33, v145 row_shr:1 row_mask:0xf bank_mask:0xf
	v_fmac_f32_dpp v110, v26, v138 row_shr:1 row_mask:0xf bank_mask:0xf
	v_fmac_f32_dpp v111, v27, v139 row_shr:1 row_mask:0xf bank_mask:0xf
	v_fmac_f32_dpp v112, v28, v140 row_shr:1 row_mask:0xf bank_mask:0xf
	v_fmac_f32_dpp v113, v29, v141 row_shr:1 row_mask:0xf bank_mask:0xf
	v_fmac_f32_dpp v106, v30, v102 row_shr:2 row_mask:0xf bank_mask:0xf
	v_fmac_f32_dpp v107, v31, v103 row_shr:2 row_mask:0xf bank_mask:0xf
	v_fmac_f32_dpp v108, v32, v104 row_shr:2 row_mask:0xf bank_mask:0xf
	v_fmac_f32_dpp v109, v33, v105 row_shr:2 row_mask:0xf bank_mask:0xf
	v_fmac_f32_dpp v110, v26, v98 row_shr:2 row_mask:0xf bank_mask:0xf
	v_fmac_f32_dpp v111, v27, v99 row_shr:2 row_mask:0xf bank_mask:0xf
	v_fmac_f32_dpp v112, v28, v100 row_shr:2 row_mask:0xf bank_mask:0xf
	v_fmac_f32_dpp v113, v29, v101 row_shr:2 row_mask:0xf bank_mask:0xf
	v_pk_mul_f32 v[114:115], v[106:107], v[106:107]
	v_pk_mul_f32 v[116:117], v[108:109], v[108:109]
	v_pk_fma_f32 v[114:115], v[114:115], v[132:133], v[196:197] op_sel_hi:[1,0,0]
	v_pk_fma_f32 v[116:117], v[116:117], v[132:133], v[196:197] op_sel_hi:[1,0,0]
	v_pk_mul_f32 v[114:115], v[106:107], v[114:115]
	v_pk_mul_f32 v[116:117], v[108:109], v[116:117]
	v_exp_f32_e32 v114, v114
	v_exp_f32_e32 v115, v115
	v_exp_f32_e32 v116, v116
	v_exp_f32_e32 v117, v117
	v_pk_add_f32 v[114:115], v[114:115], v[250:251] op_sel_hi:[1,0]
	v_pk_add_f32 v[116:117], v[116:117], v[250:251] op_sel_hi:[1,0]
	v_rcp_f32_e32 v114, v114
	v_rcp_f32_e32 v115, v115
	v_rcp_f32_e32 v116, v116
	v_rcp_f32_e32 v117, v117
	v_pk_mul_f32 v[114:115], v[106:107], v[114:115]
	v_pk_mul_f32 v[116:117], v[108:109], v[116:117]
	v_pk_mul_f32 v[114:115], v[110:111], v[114:115]
	v_pk_mul_f32 v[116:117], v[112:113], v[116:117]
	v_cvt_pk_bf16_f32 v117, v116, v117
	v_cvt_pk_bf16_f32 v116, v114, v115
	v_add_u32_e32 v130, 0x160000, v199
	v_mov_b32_e32 v114, v206
	v_mov_b32_e32 v115, v207
	s_and_saveexec_b64 s[48:49], s[10:11]
	global_store_dwordx4 v130, v[114:117], s[68:69]
	s_or_b64 exec, exec, s[48:49]
	v_pk_mul_f32 v[22:23], v[22:23], v[180:181] op_sel_hi:[1,0]
	v_pk_mul_f32 v[24:25], v[24:25], v[180:181] op_sel_hi:[1,0]
; __device__ __forceinline__ unsigned cvt_pk_bf16(float lo, float hi) { unsigned r; asm volatile("v_cvt_pk_bf16_f32 %0, %1, %2" : "=v"(r) : "v"(lo), "v"(hi)); return r; }
; __device__ __forceinline__ f32x4 gelu4(f32x4 v) { return (f32x4){gelu_t(v[0]), gelu_t(v[1]), gelu_t(v[2]), gelu_t(v[3])}; }
; template <int CTRL> __device__ __forceinline__ f32x4 dpp4(f32x4 v) { return (f32x4){dpp_f<CTRL>(v[0]), dpp_f<CTRL>(v[1]), dpp_f<CTRL>(v[2]), dpp_f<CTRL>(v[3])}; }
;     __device__ __forceinline__ void operator()(const f32x4 (&acc)[2][2][4][2], const Unit& u, int wr, int wc, int fr, int fq) const {
;     ...
;                     for (int m = 0; m < 4; ++m) {
;                         const f32x4 g = acc[ai][0][m][n] * rs[ai][m], v = acc[ai][1][m][n] * rs[ai][m];
;                         const f32x4 g1 = dpp4<0x121>(g), g2 = dpp4<0x122>(g), v1 = dpp4<0x121>(v), v2 = dpp4<0x122>(v);
;                         const f32x4 gp1 = (fr >= 1) ? g1 : pg1, gp2 = (fr >= 2) ? g2 : pg2, vp1 = (fr >= 1) ? v1 : pv1, vp2 = (fr >= 2) ? v2 : pv2;
;                         const f32x4 cgt = bg + wg0 * g + wg1 * gp1 + wg2 * gp2, cvl = bv + wv0 * v + wv1 * vp1 + wv2 * vp2;
;                         const f32x4 o = gelu4(cgt) * cvl;
;                         typedef unsigned u32x2e __attribute__((ext_vector_type(2)));
;                         u32x2e w; w.x = cvt_pk_bf16(o[0], o[1]); w.y = cvt_pk_bf16(o[2], o[3]);
;                         if (!(m == 0 && fr < 2)) *(u32x2e*)((bf16_t*)O + (size_t)(row0 + ai * HALF + m * 16) * DFFc + c) = w;
;                         pg1 = g1; pg2 = g2; pv1 = v1; pv2 = v2;
	v_pk_mul_f32 v[18:19], v[18:19], v[180:181] op_sel_hi:[1,0]
	v_pk_mul_f32 v[20:21], v[20:21], v[180:181] op_sel_hi:[1,0]
	v_pk_fma_f32 v[118:119], v[22:23], v[154:155], v[150:151]
	v_pk_fma_f32 v[120:121], v[24:25], v[156:157], v[152:153]
	v_pk_fma_f32 v[122:123], v[18:19], v[134:135], v[146:147]
	v_pk_fma_f32 v[124:125], v[20:21], v[136:137], v[148:149]
	v_fmac_f32_dpp v118, v22, v142 row_shr:1 row_mask:0xf bank_mask:0xf
	v_fmac_f32_dpp v119, v23, v143 row_shr:1 row_mask:0xf bank_mask:0xf
	v_fmac_f32_dpp v120, v24, v144 row_shr:1 row_mask:0xf bank_mask:0xf
	v_fmac_f32_dpp v121, v25, v145 row_shr:1 row_mask:0xf bank_mask:0xf
	v_fmac_f32_dpp v122, v18, v138 row_shr:1 row_mask:0xf bank_mask:0xf
	v_fmac_f32_dpp v123, v19, v139 row_shr:1 row_mask:0xf bank_mask:0xf
	v_fmac_f32_dpp v124, v20, v140 row_shr:1 row_mask:0xf bank_mask:0xf
	v_fmac_f32_dpp v125, v21, v141 row_shr:1 row_mask:0xf bank_mask:0xf
	v_fmac_f32_dpp v118, v22, v102 row_shr:2 row_mask:0xf bank_mask:0xf
	v_fmac_f32_dpp v119, v23, v103 row_shr:2 row_mask:0xf bank_mask:0xf
	v_fmac_f32_dpp v120, v24, v104 row_shr:2 row_mask:0xf bank_mask:0xf
	v_fmac_f32_dpp v121, v25, v105 row_shr:2 row_mask:0xf bank_mask:0xf
	v_fmac_f32_dpp v122, v18, v98 row_shr:2 row_mask:0xf bank_mask:0xf
	v_fmac_f32_dpp v123, v19, v99 row_shr:2 row_mask:0xf bank_mask:0xf
	v_fmac_f32_dpp v124, v20, v100 row_shr:2 row_mask:0xf bank_mask:0xf
	v_fmac_f32_dpp v125, v21, v101 row_shr:2 row_mask:0xf bank_mask:0xf
	v_fmac_f32_dpp v118, v30, v142 row_shl:15 row_mask:0xf bank_mask:0xf
	v_fmac_f32_dpp v119, v31, v143 row_shl:15 row_mask:0xf bank_mask:0xf
	v_fmac_f32_dpp v120, v32, v144 row_shl:15 row_mask:0xf bank_mask:0xf
	v_fmac_f32_dpp v121, v33, v145 row_shl:15 row_mask:0xf bank_mask:0xf
	v_fmac_f32_dpp v122, v26, v138 row_shl:15 row_mask:0xf bank_mask:0xf
	v_fmac_f32_dpp v123, v27, v139 row_shl:15 row_mask:0xf bank_mask:0xf
	v_fmac_f32_dpp v124, v28, v140 row_shl:15 row_mask:0xf bank_mask:0xf
	v_fmac_f32_dpp v125, v29, v141 row_shl:15 row_mask:0xf bank_mask:0xf
	v_fmac_f32_dpp v118, v30, v102 row_shl:14 row_mask:0xf bank_mask:0xf
	v_fmac_f32_dpp v119, v31, v103 row_shl:14 row_mask:0xf bank_mask:0xf
	v_fmac_f32_dpp v120, v32, v104 row_shl:14 row_mask:0xf bank_mask:0xf
	v_fmac_f32_dpp v121, v33, v105 row_shl:14 row_mask:0xf bank_mask:0xf
	v_fmac_f32_dpp v122, v26, v98 row_shl:14 row_mask:0xf bank_mask:0xf
	v_fmac_f32_dpp v123, v27, v99 row_shl:14 row_mask:0xf bank_mask:0xf
	v_fmac_f32_dpp v124, v28, v100 row_shl:14 row_mask:0xf bank_mask:0xf
	v_fmac_f32_dpp v125, v29, v101 row_shl:14 row_mask:0xf bank_mask:0xf
	v_pk_mul_f32 v[126:127], v[118:119], v[118:119]
	v_pk_mul_f32 v[128:129], v[120:121], v[120:121]
	v_pk_fma_f32 v[126:127], v[126:127], v[132:133], v[196:197] op_sel_hi:[1,0,0]
	v_pk_fma_f32 v[128:129], v[128:129], v[132:133], v[196:197] op_sel_hi:[1,0,0]
	v_pk_mul_f32 v[126:127], v[118:119], v[126:127]
	v_pk_mul_f32 v[128:129], v[120:121], v[128:129]
	v_exp_f32_e32 v126, v126
	v_exp_f32_e32 v127, v127
	v_exp_f32_e32 v128, v128
	v_exp_f32_e32 v129, v129
	v_pk_add_f32 v[126:127], v[126:127], v[250:251] op_sel_hi:[1,0]
	v_pk_add_f32 v[128:129], v[128:129], v[250:251] op_sel_hi:[1,0]
	v_rcp_f32_e32 v126, v126
	v_rcp_f32_e32 v127, v127
	v_rcp_f32_e32 v128, v128
	v_rcp_f32_e32 v129, v129
	v_pk_mul_f32 v[126:127], v[118:119], v[126:127]
	v_pk_mul_f32 v[128:129], v[120:121], v[128:129]
	v_pk_mul_f32 v[126:127], v[122:123], v[126:127]
	v_pk_mul_f32 v[128:129], v[124:125], v[128:129]
	v_cvt_pk_bf16_f32 v129, v128, v129
	v_cvt_pk_bf16_f32 v128, v126, v127
	v_add_u32_e32 v131, 0x18c000, v199
	v_mov_b32_e32 v126, v208
	v_mov_b32_e32 v127, v209
	global_store_dwordx4 v131, v[126:129], s[68:69]
	v_pk_mul_f32 v[14:15], v[14:15], v[200:201] op_sel_hi:[1,0]
	v_pk_mul_f32 v[16:17], v[16:17], v[200:201] op_sel_hi:[1,0]
	v_pk_mul_f32 v[10:11], v[10:11], v[200:201] op_sel_hi:[1,0]
	v_pk_mul_f32 v[12:13], v[12:13], v[200:201] op_sel_hi:[1,0]
	v_pk_fma_f32 v[106:107], v[14:15], v[154:155], v[150:151]
	v_pk_fma_f32 v[108:109], v[16:17], v[156:157], v[152:153]
	v_pk_fma_f32 v[110:111], v[10:11], v[134:135], v[146:147]
	v_pk_fma_f32 v[112:113], v[12:13], v[136:137], v[148:149]
	v_fmac_f32_dpp v106, v14, v142 row_shr:1 row_mask:0xf bank_mask:0xf
	v_fmac_f32_dpp v107, v15, v143 row_shr:1 row_mask:0xf bank_mask:0xf
	v_fmac_f32_dpp v108, v16, v144 row_shr:1 row_mask:0xf bank_mask:0xf
	v_fmac_f32_dpp v109, v17, v145 row_shr:1 row_mask:0xf bank_mask:0xf
	v_fmac_f32_dpp v110, v10, v138 row_shr:1 row_mask:0xf bank_mask:0xf
	v_fmac_f32_dpp v111, v11, v139 row_shr:1 row_mask:0xf bank_mask:0xf
	v_fmac_f32_dpp v112, v12, v140 row_shr:1 row_mask:0xf bank_mask:0xf
	v_fmac_f32_dpp v113, v13, v141 row_shr:1 row_mask:0xf bank_mask:0xf
	v_fmac_f32_dpp v106, v14, v102 row_shr:2 row_mask:0xf bank_mask:0xf
	v_fmac_f32_dpp v107, v15, v103 row_shr:2 row_mask:0xf bank_mask:0xf
	v_fmac_f32_dpp v108, v16, v104 row_shr:2 row_mask:0xf bank_mask:0xf
	v_fmac_f32_dpp v109, v17, v105 row_shr:2 row_mask:0xf bank_mask:0xf
	v_fmac_f32_dpp v110, v10, v98 row_shr:2 row_mask:0xf bank_mask:0xf
	v_fmac_f32_dpp v111, v11, v99 row_shr:2 row_mask:0xf bank_mask:0xf
	v_fmac_f32_dpp v112, v12, v100 row_shr:2 row_mask:0xf bank_mask:0xf
	v_fmac_f32_dpp v113, v13, v101 row_shr:2 row_mask:0xf bank_mask:0xf
	v_fmac_f32_dpp v106, v22, v142 row_shl:15 row_mask:0xf bank_mask:0xf
	v_fmac_f32_dpp v107, v23, v143 row_shl:15 row_mask:0xf bank_mask:0xf
	v_fmac_f32_dpp v108, v24, v144 row_shl:15 row_mask:0xf bank_mask:0xf
	v_fmac_f32_dpp v109, v25, v145 row_shl:15 row_mask:0xf bank_mask:0xf
	v_fmac_f32_dpp v110, v18, v138 row_shl:15 row_mask:0xf bank_mask:0xf
; __device__ __forceinline__ unsigned cvt_pk_bf16(float lo, float hi) { unsigned r; asm volatile("v_cvt_pk_bf16_f32 %0, %1, %2" : "=v"(r) : "v"(lo), "v"(hi)); return r; }
; __device__ __forceinline__ f32x4 gelu4(f32x4 v) { return (f32x4){gelu_t(v[0]), gelu_t(v[1]), gelu_t(v[2]), gelu_t(v[3])}; }
; template <int CTRL> __device__ __forceinline__ f32x4 dpp4(f32x4 v) { return (f32x4){dpp_f<CTRL>(v[0]), dpp_f<CTRL>(v[1]), dpp_f<CTRL>(v[2]), dpp_f<CTRL>(v[3])}; }
; #define PG8_BAR __builtin_amdgcn_s_barrier()
;     __device__ __forceinline__ void operator()(const f32x4 (&acc)[2][2][4][2], const Unit& u, int wr, int wc, int fr, int fq) const {
;     ...
;                     for (int m = 0; m < 4; ++m) {
;                         const f32x4 g = acc[ai][0][m][n] * rs[ai][m], v = acc[ai][1][m][n] * rs[ai][m];
;                         const f32x4 g1 = dpp4<0x121>(g), g2 = dpp4<0x122>(g), v1 = dpp4<0x121>(v), v2 = dpp4<0x122>(v);
;                         const f32x4 gp1 = (fr >= 1) ? g1 : pg1, gp2 = (fr >= 2) ? g2 : pg2, vp1 = (fr >= 1) ? v1 : pv1, vp2 = (fr >= 2) ? v2 : pv2;
;                         const f32x4 cgt = bg + wg0 * g + wg1 * gp1 + wg2 * gp2, cvl = bv + wv0 * v + wv1 * vp1 + wv2 * vp2;
;                         const f32x4 o = gelu4(cgt) * cvl;
;                         typedef unsigned u32x2e __attribute__((ext_vector_type(2)));
;                         u32x2e w; w.x = cvt_pk_bf16(o[0], o[1]); w.y = cvt_pk_bf16(o[2], o[3]);
;                         if (!(m == 0 && fr < 2)) *(u32x2e*)((bf16_t*)O + (size_t)(row0 + ai * HALF + m * 16) * DFFc + c) = w;
;                         pg1 = g1; pg2 = g2; pv1 = v1; pv2 = v2;
; template <class Epi, class Sched, bool ALIGN_EPI = false, bool SP2 = false>
; __device__ __forceinline__ void gemm_phase(PG8_LAS unsigned char* lds, const Gemm g, const Sched& S, const Epi& E, int wave_in) {
;     ...
;         if constexpr (!Epi::AFTER_DRAIN) { E(acc, cur, wr, wc, fr, fq); S.done(cur); }
;         if (!has_next) break;
; #pragma unroll
;         for (int a = 0; a < 2; ++a)
; #pragma unroll
;             for (int b = 0; b < 2; ++b)
; #pragma unroll
;                 for (int m = 0; m < 4; ++m)
; #pragma unroll
;                     for (int n = 0; n < 2; ++n) acc[a][b][m][n] = (f32x4){0.f, 0.f, 0.f, 0.f};
;         cur = nxt; cA = nA; cB = nB; ++ui;
;         if constexpr (ALIGN_EPI) { if (wr == 1) PG8_BAR; }
	v_fmac_f32_dpp v111, v19, v139 row_shl:15 row_mask:0xf bank_mask:0xf
	v_fmac_f32_dpp v112, v20, v140 row_shl:15 row_mask:0xf bank_mask:0xf
	v_fmac_f32_dpp v113, v21, v141 row_shl:15 row_mask:0xf bank_mask:0xf
	v_fmac_f32_dpp v106, v22, v102 row_shl:14 row_mask:0xf bank_mask:0xf
	v_fmac_f32_dpp v107, v23, v103 row_shl:14 row_mask:0xf bank_mask:0xf
	v_fmac_f32_dpp v108, v24, v104 row_shl:14 row_mask:0xf bank_mask:0xf
	v_fmac_f32_dpp v109, v25, v105 row_shl:14 row_mask:0xf bank_mask:0xf
	v_fmac_f32_dpp v110, v18, v98 row_shl:14 row_mask:0xf bank_mask:0xf
	v_fmac_f32_dpp v111, v19, v99 row_shl:14 row_mask:0xf bank_mask:0xf
	v_fmac_f32_dpp v112, v20, v100 row_shl:14 row_mask:0xf bank_mask:0xf
	v_fmac_f32_dpp v113, v21, v101 row_shl:14 row_mask:0xf bank_mask:0xf
	v_pk_mul_f32 v[114:115], v[106:107], v[106:107]
	v_pk_mul_f32 v[116:117], v[108:109], v[108:109]
	v_pk_fma_f32 v[114:115], v[114:115], v[132:133], v[196:197] op_sel_hi:[1,0,0]
	v_pk_fma_f32 v[116:117], v[116:117], v[132:133], v[196:197] op_sel_hi:[1,0,0]
	v_pk_mul_f32 v[114:115], v[106:107], v[114:115]
	v_pk_mul_f32 v[116:117], v[108:109], v[116:117]
	v_exp_f32_e32 v114, v114
	v_exp_f32_e32 v115, v115
	v_exp_f32_e32 v116, v116
	v_exp_f32_e32 v117, v117
	v_pk_add_f32 v[114:115], v[114:115], v[250:251] op_sel_hi:[1,0]
	v_pk_add_f32 v[116:117], v[116:117], v[250:251] op_sel_hi:[1,0]
	v_rcp_f32_e32 v114, v114
	v_rcp_f32_e32 v115, v115
	v_rcp_f32_e32 v116, v116
	v_rcp_f32_e32 v117, v117
	v_pk_mul_f32 v[114:115], v[106:107], v[114:115]
	v_pk_mul_f32 v[116:117], v[108:109], v[116:117]
	v_pk_mul_f32 v[114:115], v[110:111], v[114:115]
	v_pk_mul_f32 v[116:117], v[112:113], v[116:117]
	v_cvt_pk_bf16_f32 v117, v116, v117
	v_cvt_pk_bf16_f32 v116, v114, v115
	v_add_u32_e32 v130, 0x1b8000, v199
	v_mov_b32_e32 v114, v210
	v_mov_b32_e32 v115, v211
	global_store_dwordx4 v130, v[114:117], s[68:69]
	v_pk_mul_f32 v[6:7], v[6:7], v[178:179] op_sel_hi:[1,0]
	v_pk_mul_f32 v[8:9], v[8:9], v[178:179] op_sel_hi:[1,0]
	v_pk_mul_f32 v[2:3], v[2:3], v[178:179] op_sel_hi:[1,0]
	v_pk_mul_f32 v[4:5], v[4:5], v[178:179] op_sel_hi:[1,0]
	v_pk_fma_f32 v[118:119], v[6:7], v[154:155], v[150:151]
	v_pk_fma_f32 v[120:121], v[8:9], v[156:157], v[152:153]
	v_pk_fma_f32 v[122:123], v[2:3], v[134:135], v[146:147]
	v_pk_fma_f32 v[124:125], v[4:5], v[136:137], v[148:149]
	v_fmac_f32_dpp v118, v6, v142 row_shr:1 row_mask:0xf bank_mask:0xf
	v_fmac_f32_dpp v119, v7, v143 row_shr:1 row_mask:0xf bank_mask:0xf
	v_fmac_f32_dpp v120, v8, v144 row_shr:1 row_mask:0xf bank_mask:0xf
	v_fmac_f32_dpp v121, v9, v145 row_shr:1 row_mask:0xf bank_mask:0xf
	v_fmac_f32_dpp v122, v2, v138 row_shr:1 row_mask:0xf bank_mask:0xf
	v_fmac_f32_dpp v123, v3, v139 row_shr:1 row_mask:0xf bank_mask:0xf
	v_fmac_f32_dpp v124, v4, v140 row_shr:1 row_mask:0xf bank_mask:0xf
	v_fmac_f32_dpp v125, v5, v141 row_shr:1 row_mask:0xf bank_mask:0xf
	v_fmac_f32_dpp v118, v6, v102 row_shr:2 row_mask:0xf bank_mask:0xf
	v_fmac_f32_dpp v119, v7, v103 row_shr:2 row_mask:0xf bank_mask:0xf
	v_fmac_f32_dpp v120, v8, v104 row_shr:2 row_mask:0xf bank_mask:0xf
	v_fmac_f32_dpp v121, v9, v105 row_shr:2 row_mask:0xf bank_mask:0xf
	v_fmac_f32_dpp v122, v2, v98 row_shr:2 row_mask:0xf bank_mask:0xf
	v_fmac_f32_dpp v123, v3, v99 row_shr:2 row_mask:0xf bank_mask:0xf
	v_fmac_f32_dpp v124, v4, v100 row_shr:2 row_mask:0xf bank_mask:0xf
	v_fmac_f32_dpp v125, v5, v101 row_shr:2 row_mask:0xf bank_mask:0xf
	v_fmac_f32_dpp v118, v14, v142 row_shl:15 row_mask:0xf bank_mask:0xf
	v_fmac_f32_dpp v119, v15, v143 row_shl:15 row_mask:0xf bank_mask:0xf
	v_fmac_f32_dpp v120, v16, v144 row_shl:15 row_mask:0xf bank_mask:0xf
	v_fmac_f32_dpp v121, v17, v145 row_shl:15 row_mask:0xf bank_mask:0xf
	v_fmac_f32_dpp v122, v10, v138 row_shl:15 row_mask:0xf bank_mask:0xf
	v_fmac_f32_dpp v123, v11, v139 row_shl:15 row_mask:0xf bank_mask:0xf
	v_fmac_f32_dpp v124, v12, v140 row_shl:15 row_mask:0xf bank_mask:0xf
	v_fmac_f32_dpp v125, v13, v141 row_shl:15 row_mask:0xf bank_mask:0xf
	v_fmac_f32_dpp v118, v14, v102 row_shl:14 row_mask:0xf bank_mask:0xf
	v_fmac_f32_dpp v119, v15, v103 row_shl:14 row_mask:0xf bank_mask:0xf
	v_fmac_f32_dpp v120, v16, v104 row_shl:14 row_mask:0xf bank_mask:0xf
	v_fmac_f32_dpp v121, v17, v105 row_shl:14 row_mask:0xf bank_mask:0xf
	v_fmac_f32_dpp v122, v10, v98 row_shl:14 row_mask:0xf bank_mask:0xf
	v_fmac_f32_dpp v123, v11, v99 row_shl:14 row_mask:0xf bank_mask:0xf
	v_fmac_f32_dpp v124, v12, v100 row_shl:14 row_mask:0xf bank_mask:0xf
	v_fmac_f32_dpp v125, v13, v101 row_shl:14 row_mask:0xf bank_mask:0xf
	v_pk_mul_f32 v[126:127], v[118:119], v[118:119]
	v_pk_mul_f32 v[128:129], v[120:121], v[120:121]
	v_pk_fma_f32 v[126:127], v[126:127], v[132:133], v[196:197] op_sel_hi:[1,0,0]
	v_pk_fma_f32 v[128:129], v[128:129], v[132:133], v[196:197] op_sel_hi:[1,0,0]
	v_pk_mul_f32 v[126:127], v[118:119], v[126:127]
	v_pk_mul_f32 v[128:129], v[120:121], v[128:129]
	v_exp_f32_e32 v126, v126
	v_exp_f32_e32 v127, v127
	v_exp_f32_e32 v128, v128
	v_exp_f32_e32 v129, v129
	v_pk_add_f32 v[126:127], v[126:127], v[250:251] op_sel_hi:[1,0]
	v_pk_add_f32 v[128:129], v[128:129], v[250:251] op_sel_hi:[1,0]
	v_rcp_f32_e32 v126, v126
	v_rcp_f32_e32 v127, v127
	v_rcp_f32_e32 v128, v128
	v_rcp_f32_e32 v129, v129
	v_pk_mul_f32 v[126:127], v[118:119], v[126:127]
	v_pk_mul_f32 v[128:129], v[120:121], v[128:129]
	v_pk_mul_f32 v[126:127], v[122:123], v[126:127]
	v_pk_mul_f32 v[128:129], v[124:125], v[128:129]
	v_cvt_pk_bf16_f32 v129, v128, v129
	v_cvt_pk_bf16_f32 v128, v126, v127
	v_add_u32_e32 v131, 0x1e4000, v199
	v_mov_b32_e32 v126, v133
	v_mov_b32_e32 v127, v251
	global_store_dwordx4 v131, v[126:129], s[68:69]
	s_andn2_b64 vcc, exec, s[8:9]
	s_mov_b64 s[8:9], -1
	s_cbranch_vccnz .LBB0_39
	s_andn2_b64 vcc, exec, s[2:3]
	s_cbranch_vccnz .LBB0_38
	s_barrier
	s_branch .LBB0_38
